# GLA pass A/C staging and gate load ladders de-serialized (loads issued together, single wait)
# speedup vs baseline: 1.0011x; 1.0011x over previous
.LBB0_673:
	v_add_u32_e32 v0, s48, v78
	s_and_b32 s22, s16, 1
	v_ashrrev_i32_e32 v1, 31, v0
	v_lshlrev_b64 v[2:3], 10, v[0:1]
	s_lshl_b32 s16, s22, 8
	v_mad_i64_i32 v[0:1], s[60:61], v0, s3, v[74:75]
	v_lshl_add_u64 v[0:1], v[0:1], 0, s[16:17]
	v_lshl_add_u64 v[4:5], v[0:1], 0, v[64:65]
	v_add_co_u32_e32 v0, vcc, s28, v4
	v_lshl_add_u64 v[2:3], s[14:15], 0, v[2:3]
	s_nop 0
	v_addc_co_u32_e32 v1, vcc, 0, v5, vcc
	v_add_co_u32_e32 v6, vcc, s29, v4
	v_lshl_add_u64 v[2:3], v[2:3], 0, s[16:17]
	s_nop 0
	v_addc_co_u32_e32 v7, vcc, 0, v5, vcc
	v_add_co_u32_e32 v8, vcc, s30, v4
	v_lshl_add_u64 v[2:3], v[2:3], 0, v[64:65]
	s_nop 0
	v_addc_co_u32_e32 v9, vcc, 0, v5, vcc
	flat_load_ushort v12, v[2:3]
	flat_load_ushort v13, v[2:3] offset:1024
	flat_load_ushort v14, v[0:1] offset:3072
	flat_load_ushort v15, v[2:3] offset:2048
	flat_load_ushort v16, v[6:7] offset:1024
	flat_load_ushort v17, v[8:9] offset:3072
	flat_load_ushort v18, v[2:3] offset:3072
	v_add_co_u32_e32 v0, vcc, s28, v2
	s_lshl_b32 s16, s22, 9
	s_nop 0
	v_addc_co_u32_e32 v1, vcc, 0, v3, vcc
	v_add_co_u32_e32 v6, vcc, s33, v4
	s_nop 1
	v_addc_co_u32_e32 v7, vcc, 0, v5, vcc
	v_add_co_u32_e32 v8, vcc, s34, v4
	s_nop 1
	v_addc_co_u32_e32 v9, vcc, 0, v5, vcc
	v_add_co_u32_e32 v10, vcc, s35, v4
	s_nop 1
	v_addc_co_u32_e32 v11, vcc, 0, v5, vcc
	flat_load_ushort v19, v[0:1]
	flat_load_ushort v20, v[0:1] offset:1024
	flat_load_ushort v21, v[6:7] offset:3072
	flat_load_ushort v22, v[0:1] offset:2048
	flat_load_ushort v23, v[8:9] offset:1024
	flat_load_ushort v24, v[10:11] offset:3072
	flat_load_ushort v25, v[0:1] offset:3072
	v_add_co_u32_e32 v0, vcc, s36, v2
	s_waitcnt vmcnt(0) lgkmcnt(0)
	v_lshlrev_b32_e32 v21, 16, v21
	v_addc_co_u32_e32 v1, vcc, 0, v3, vcc
	v_add_co_u32_e32 v6, vcc, s38, v4
	v_lshlrev_b32_e32 v23, 16, v23
	s_nop 0
	v_addc_co_u32_e32 v7, vcc, 0, v5, vcc
	v_add_co_u32_e32 v8, vcc, s39, v4
	v_lshlrev_b32_e32 v24, 16, v24
	s_nop 0
	v_addc_co_u32_e32 v9, vcc, 0, v5, vcc
	v_add_co_u32_e32 v10, vcc, s40, v4
	s_nop 1
	v_addc_co_u32_e32 v11, vcc, 0, v5, vcc
	flat_load_ushort v26, v[0:1]
	flat_load_ushort v27, v[0:1] offset:1024
	flat_load_ushort v28, v[6:7] offset:3072
	flat_load_ushort v29, v[0:1] offset:2048
	flat_load_ushort v30, v[8:9] offset:1024
	s_nop 0
	flat_load_ushort v10, v[10:11] offset:3072
	s_nop 0
	flat_load_ushort v11, v[0:1] offset:3072
	v_add_co_u32_e32 v0, vcc, s29, v2
	s_waitcnt vmcnt(0) lgkmcnt(0)
	v_lshlrev_b32_e32 v28, 16, v28
	v_addc_co_u32_e32 v1, vcc, 0, v3, vcc
	v_add_co_u32_e32 v2, vcc, s42, v4
	v_lshlrev_b32_e32 v30, 16, v30
	s_nop 0
	v_addc_co_u32_e32 v3, vcc, 0, v5, vcc
	v_add_co_u32_e32 v6, vcc, s43, v4
	v_lshlrev_b32_e32 v10, 16, v10
	s_nop 0
	v_addc_co_u32_e32 v7, vcc, 0, v5, vcc
	v_add_co_u32_e32 v8, vcc, s44, v4
	s_nop 1
	v_addc_co_u32_e32 v9, vcc, 0, v5, vcc
	flat_load_ushort v31, v[0:1]
	flat_load_ushort v32, v[0:1] offset:1024
	flat_load_ushort v33, v[2:3] offset:3072
	s_nop 0
	flat_load_ushort v2, v[0:1] offset:2048
	flat_load_ushort v34, v[6:7] offset:1024
	s_nop 0
	flat_load_ushort v8, v[8:9] offset:3072
	s_nop 0
	flat_load_ushort v0, v[0:1] offset:3072
	v_cvt_f32_f16_e32 v1, v12
	v_cvt_f32_f16_e32 v3, v13
	v_cvt_f32_f16_e32 v6, v15
	v_cvt_f32_f16_e32 v7, v18
	v_add_f32_e32 v9, 0, v1
	v_cvt_f32_f16_e32 v1, v19
	v_add_f32_e32 v12, v9, v3
	v_cvt_f32_f16_e32 v3, v20
	v_add_f32_e32 v13, v12, v6
	v_cvt_f32_f16_e32 v6, v22
	v_add_f32_e32 v15, v13, v7
	v_cvt_f32_f16_e32 v7, v25
	v_add_f32_e32 v18, v15, v1
	v_cvt_f32_f16_e32 v1, v26
	v_add_f32_e32 v19, v18, v3
	v_cvt_f32_f16_e32 v3, v27
	v_add_f32_e32 v20, v19, v6
	v_cvt_f32_f16_e32 v6, v29
	v_add_f32_e32 v22, v20, v7
	v_cvt_f32_f16_e32 v7, v11
	v_add_f32_e32 v11, v22, v1
	v_add_f32_e32 v25, v11, v3
	v_add_f32_e32 v26, v25, v6
	v_add_f32_e32 v27, v26, v7
	v_add_co_u32_e32 v6, vcc, s31, v4
	s_waitcnt vmcnt(0) lgkmcnt(0)
	v_cvt_f32_f16_e32 v1, v31
	v_cvt_f32_f16_e32 v3, v32
	v_addc_co_u32_e32 v7, vcc, 0, v5, vcc
	v_cvt_f32_f16_e32 v2, v2
	v_add_f32_e32 v29, v27, v1
	v_cvt_f32_f16_e32 v0, v0
	v_add_f32_e32 v31, v29, v3
	v_add_f32_e32 v32, v31, v2
	v_lshlrev_b32_e32 v33, 16, v33
	v_add_f32_e32 v35, v32, v0
	v_add_u32_e32 v0, s48, v81
	v_mad_i64_i32 v[0:1], s[60:61], v0, s3, v[74:75]
	v_lshl_add_u64 v[0:1], v[0:1], 0, s[16:17]
	ds_write_b32 v79, v35 offset:57344
	v_lshl_add_u64 v[0:1], v[0:1], 0, v[72:73]
	flat_load_dwordx4 v[0:3], v[0:1] offset:2048
	s_nop 0
	flat_load_ushort v36, v[4:5] offset:1024
	flat_load_ushort v37, v[6:7] offset:1024
	v_add_co_u32_e32 v6, vcc, s37, v4
	v_lshlrev_b32_e32 v34, 16, v34
	s_nop 0
	v_addc_co_u32_e32 v7, vcc, 0, v5, vcc
	v_add_co_u32_e32 v4, vcc, s41, v4
	flat_load_ushort v6, v[6:7] offset:1024
	s_nop 0
	v_addc_co_u32_e32 v5, vcc, 0, v5, vcc
	flat_load_ushort v7, v[4:5] offset:1024
	v_add_u32_e32 v4, s48, v82
	v_mad_i64_i32 v[4:5], s[22:23], v4, s3, v[74:75]
	v_lshl_add_u64 v[4:5], v[4:5], 0, s[16:17]
	v_lshl_add_u64 v[4:5], v[4:5], 0, v[72:73]
	flat_load_dwordx4 v[184:187], v[4:5] offset:2048
	v_add_u32_e32 v4, s48, v83
	v_mad_i64_i32 v[4:5], s[22:23], v4, s3, v[74:75]
	v_lshl_add_u64 v[4:5], v[4:5], 0, s[16:17]
	v_lshl_add_u64 v[4:5], v[4:5], 0, v[72:73]
	flat_load_dwordx4 v[188:191], v[4:5] offset:2048
	v_add_u32_e32 v4, s48, v84
	v_mad_i64_i32 v[4:5], s[22:23], v4, s3, v[74:75]
	v_lshl_add_u64 v[4:5], v[4:5], 0, s[16:17]
	v_lshl_add_u64 v[4:5], v[4:5], 0, v[72:73]
	flat_load_dwordx4 v[192:195], v[4:5] offset:2048
	v_lshlrev_b32_e32 v8, 16, v8
	s_waitcnt vmcnt(0) lgkmcnt(0)
	ds_write_b128 v93, v[0:3] offset:20480
	v_lshlrev_b32_e32 v6, 16, v6
	v_lshlrev_b32_e32 v7, 16, v7
	ds_write_b128 v94, v[184:187] offset:20480
	ds_write_b128 v93, v[188:191] offset:38912
	v_lshlrev_b32_e32 v4, 16, v36
	v_lshlrev_b32_e32 v5, 16, v14
	v_lshlrev_b32_e32 v14, 16, v16
	v_lshlrev_b32_e32 v16, 16, v17
	v_lshlrev_b32_e32 v17, 16, v37
	ds_write_b128 v95, v[192:195] offset:20480
	s_waitcnt lgkmcnt(0)
	s_barrier
	ds_read2st64_b32 v[0:1], v80 offset0:224 offset1:226
	ds_read2st64_b32 v[2:3], v80 offset0:228 offset1:230
	s_waitcnt lgkmcnt(1)
	v_add_f32_e32 v0, 0, v0
	v_cndmask_b32_e64 v36, v0, 0, s[6:7]
	v_add_f32_e32 v0, v0, v1
	v_add_f32_e32 v1, v1, v36
	v_cndmask_b32_e64 v1, v36, v1, s[8:9]
	s_waitcnt lgkmcnt(0)
	v_add_f32_e32 v0, v0, v2
	v_add_f32_e32 v2, v2, v1
	v_cndmask_b32_e64 v1, v1, v2, s[10:11]
	v_add_f32_e32 v2, v3, v1
	v_cndmask_b32_e64 v1, v1, v2, s[12:13]
	v_add_f32_e32 v0, v0, v3
	v_add_f32_e32 v2, v9, v1
	v_add_f32_e32 v3, v12, v1
	v_add_f32_e32 v9, v13, v1
	v_add_f32_e32 v12, v15, v1
	v_add_f32_e32 v13, v18, v1
	v_add_f32_e32 v15, v19, v1
	v_add_f32_e32 v18, v20, v1
	v_add_f32_e32 v19, v22, v1
	v_add_f32_e32 v11, v11, v1
	v_add_f32_e32 v20, v25, v1
	v_add_f32_e32 v22, v26, v1
	v_add_f32_e32 v25, v27, v1
	v_add_f32_e32 v26, v29, v1
	v_add_f32_e32 v27, v31, v1
	v_add_f32_e32 v29, v32, v1
	v_add_f32_e32 v1, v35, v1
	v_sub_f32_e32 v2, v0, v2
	v_sub_f32_e32 v3, v0, v3
	v_sub_f32_e32 v9, v0, v9
	v_sub_f32_e32 v12, v0, v12
	v_sub_f32_e32 v13, v0, v13
	v_sub_f32_e32 v15, v0, v15
	v_sub_f32_e32 v18, v0, v18
	v_sub_f32_e32 v19, v0, v19
	v_sub_f32_e32 v11, v0, v11
	v_sub_f32_e32 v20, v0, v20
	v_sub_f32_e32 v22, v0, v22
	v_sub_f32_e32 v25, v0, v25
	v_sub_f32_e32 v26, v0, v26
	v_sub_f32_e32 v27, v0, v27
	v_sub_f32_e32 v29, v0, v29
	v_sub_f32_e32 v1, v0, v1
	v_mul_f32_e32 v2, 0x3fb8aa3b, v2
	v_mul_f32_e32 v3, 0x3fb8aa3b, v3
	v_mul_f32_e32 v9, 0x3fb8aa3b, v9
	v_mul_f32_e32 v12, 0x3fb8aa3b, v12
	v_mul_f32_e32 v13, 0x3fb8aa3b, v13
	v_mul_f32_e32 v15, 0x3fb8aa3b, v15
	v_mul_f32_e32 v18, 0x3fb8aa3b, v18
	v_mul_f32_e32 v19, 0x3fb8aa3b, v19
	v_mul_f32_e32 v11, 0x3fb8aa3b, v11
	v_mul_f32_e32 v20, 0x3fb8aa3b, v20
	v_mul_f32_e32 v22, 0x3fb8aa3b, v22
	v_mul_f32_e32 v25, 0x3fb8aa3b, v25
	v_mul_f32_e32 v26, 0x3fb8aa3b, v26
	v_mul_f32_e32 v27, 0x3fb8aa3b, v27
	v_mul_f32_e32 v29, 0x3fb8aa3b, v29
	v_mul_f32_e32 v1, 0x3fb8aa3b, v1
	v_exp_f32_e32 v2, v2
	v_exp_f32_e32 v3, v3
	v_exp_f32_e32 v9, v9
	v_exp_f32_e32 v12, v12
	v_exp_f32_e32 v13, v13
	v_exp_f32_e32 v15, v15
	v_exp_f32_e32 v18, v18
	v_exp_f32_e32 v19, v19
	v_exp_f32_e32 v11, v11
	v_exp_f32_e32 v20, v20
	v_exp_f32_e32 v22, v22
	v_exp_f32_e32 v25, v25
	v_exp_f32_e32 v26, v26
	v_exp_f32_e32 v27, v27
	v_exp_f32_e32 v29, v29
	v_exp_f32_e32 v1, v1
	v_mul_f32_e32 v2, v2, v4
	v_mul_f32_e32 v3, v3, v5
	v_mul_f32_e32 v4, v9, v14
	v_mul_f32_e32 v5, v12, v16
	v_mul_f32_e32 v9, v13, v17
	v_mul_f32_e32 v12, v15, v21
	v_mul_f32_e32 v13, v18, v23
	v_mul_f32_e32 v14, v19, v24
	v_mul_f32_e32 v6, v11, v6
	v_mul_f32_e32 v11, v20, v28
	v_mul_f32_e32 v15, v22, v30
	v_mul_f32_e32 v10, v25, v10
	v_mul_f32_e32 v7, v26, v7
	v_mul_f32_e32 v16, v27, v33
	v_mul_f32_e32 v17, v29, v34
	v_mul_f32_e32 v1, v1, v8
	v_bfe_u32 v8, v2, 16, 1
	v_bfe_u32 v18, v3, 16, 1
	v_bfe_u32 v19, v4, 16, 1
	v_bfe_u32 v20, v5, 16, 1
	v_bfe_u32 v21, v9, 16, 1
	v_bfe_u32 v22, v12, 16, 1
	v_bfe_u32 v23, v13, 16, 1
	v_bfe_u32 v24, v14, 16, 1
	v_bfe_u32 v25, v6, 16, 1
	v_bfe_u32 v26, v11, 16, 1
	v_bfe_u32 v27, v15, 16, 1
	v_bfe_u32 v28, v10, 16, 1
	v_bfe_u32 v29, v7, 16, 1
	v_bfe_u32 v30, v16, 16, 1
	v_bfe_u32 v31, v17, 16, 1
	v_bfe_u32 v32, v1, 16, 1
	v_add3_u32 v2, v2, v8, s45
	v_add3_u32 v3, v3, v18, s45
	v_add3_u32 v4, v4, v19, s45
	v_add3_u32 v5, v5, v20, s45
	v_add3_u32 v8, v9, v21, s45
	v_add3_u32 v9, v12, v22, s45
	v_add3_u32 v12, v13, v23, s45
	v_add3_u32 v13, v14, v24, s45
	v_add3_u32 v6, v6, v25, s45
	v_add3_u32 v11, v11, v26, s45
	v_add3_u32 v14, v15, v27, s45
	v_add3_u32 v10, v10, v28, s45
	v_add3_u32 v7, v7, v29, s45
	v_add3_u32 v15, v16, v30, s45
	v_add3_u32 v16, v17, v31, s45
	v_add3_u32 v1, v1, v32, s45
	ds_write_b16_d16_hi v96, v2
	ds_write_b16_d16_hi v96, v3 offset:320
	ds_write_b16_d16_hi v96, v4 offset:640
	ds_write_b16_d16_hi v96, v5 offset:960
	ds_write_b16_d16_hi v96, v8 offset:1280
	ds_write_b16_d16_hi v96, v9 offset:1600
	ds_write_b16_d16_hi v96, v12 offset:1920
	ds_write_b16_d16_hi v96, v13 offset:2240
	ds_write_b16_d16_hi v96, v6 offset:2560
	ds_write_b16_d16_hi v96, v11 offset:2880
	ds_write_b16_d16_hi v96, v14 offset:3200
	ds_write_b16_d16_hi v96, v10 offset:3520
	ds_write_b16_d16_hi v96, v7 offset:3840
	ds_write_b16_d16_hi v96, v15 offset:4160
	ds_write_b16_d16_hi v96, v16 offset:4480
	ds_write_b16_d16_hi v96, v1 offset:4800
	s_and_saveexec_b64 s[22:23], s[6:7]
	s_cbranch_execz .LBB0_668
	v_mul_f32_e32 v0, 0x3fb8aa3b, v0
	v_exp_f32_e32 v2, v0
	v_lshl_add_u64 v[0:1], s[50:51], 0, v[66:67]
	flat_store_dword v[0:1], v2
	s_branch .LBB0_668

.LBB0_1056:
	v_add_u32_e32 v2, v65, v75
	s_waitcnt lgkmcnt(0)
	s_barrier
	ds_read_b64_tr_b16 v[0:1], v2 offset:34816
	ds_read_b64_tr_b16 v[2:3], v2 offset:37120
	ds_read_b128 v[4:7], v88
	v_add_u32_e32 v34, v65, v76
	s_waitcnt lgkmcnt(0)
	v_mfma_f32_32x32x16_bf16 v[16:31], v[4:7], v[0:3], 0
	ds_read_b128 v[4:7], v88 offset:4608
	ds_read_b64_tr_b16 v[32:33], v34 offset:34816
	ds_read_b64_tr_b16 v[34:35], v34 offset:37120
	ds_read_b128 v[56:59], v89
	s_lshl_b32 s66, s66, 1
	s_add_i32 s78, s78, s54
	s_add_i32 s59, s59, s81
	s_add_i32 s82, s82, s83
	v_lshl_add_u64 v[42:43], v[42:43], 0, s[72:73]
	s_waitcnt lgkmcnt(0)
	v_mfma_f32_32x32x16_bf16 v[16:31], v[56:59], v[32:35], v[16:31]
	ds_read_b128 v[56:59], v89 offset:4608
	v_lshl_add_u64 v[44:45], v[44:45], 0, s[72:73]
	v_lshl_add_u64 v[46:47], v[46:47], 0, s[72:73]
	v_lshl_add_u64 v[48:49], v[48:49], 0, s[72:73]
	v_lshl_add_u64 v[50:51], v[50:51], 0, s[72:73]
	s_cmpk_lt_i32 s78, 0x440
	v_mfma_f32_32x32x16_bf16 v[0:15], v[4:7], v[0:3], 0
	s_waitcnt lgkmcnt(0)
	v_mfma_f32_32x32x16_bf16 v[0:15], v[56:59], v[32:35], v[0:15]
	v_add_u32_e32 v34, v65, v77
	ds_read_b64_tr_b16 v[32:33], v34 offset:34816
	ds_read_b64_tr_b16 v[34:35], v34 offset:37120
	ds_read_b128 v[56:59], v90
	s_waitcnt lgkmcnt(0)
	v_mfma_f32_32x32x16_bf16 v[16:31], v[56:59], v[32:35], v[16:31]
	ds_read_b128 v[56:59], v90 offset:4608
	s_waitcnt lgkmcnt(0)
	v_mfma_f32_32x32x16_bf16 v[0:15], v[56:59], v[32:35], v[0:15]
	v_add_u32_e32 v34, v65, v78
	ds_read_b64_tr_b16 v[32:33], v34 offset:34816
	ds_read_b64_tr_b16 v[34:35], v34 offset:37120
	ds_read_b128 v[56:59], v91
	s_waitcnt lgkmcnt(0)
	v_mfma_f32_32x32x16_bf16 v[16:31], v[56:59], v[32:35], v[16:31]
	ds_read_b128 v[56:59], v91 offset:4608
	s_waitcnt lgkmcnt(0)
	v_mfma_f32_32x32x16_bf16 v[0:15], v[56:59], v[32:35], v[0:15]
	v_add_u32_e32 v34, v66, v75
	ds_read_b64_tr_b16 v[32:33], v34
	ds_read_b64_tr_b16 v[34:35], v34 offset:2304
	ds_read_b128 v[56:59], v92
	s_waitcnt lgkmcnt(0)
	v_mfma_f32_32x32x16_bf16 v[16:31], v[56:59], v[32:35], v[16:31]
	ds_read_b128 v[56:59], v92 offset:8704
	s_waitcnt lgkmcnt(0)
	v_mfma_f32_32x32x16_bf16 v[0:15], v[56:59], v[32:35], v[0:15]
	v_add_u32_e32 v34, v66, v76
	ds_read_b64_tr_b16 v[32:33], v34
	ds_read_b64_tr_b16 v[34:35], v34 offset:2304
	ds_read_b128 v[56:59], v93
	s_waitcnt lgkmcnt(0)
	v_mfma_f32_32x32x16_bf16 v[16:31], v[56:59], v[32:35], v[16:31]
	ds_read_b128 v[56:59], v93 offset:8704
	s_waitcnt lgkmcnt(0)
	v_mfma_f32_32x32x16_bf16 v[0:15], v[56:59], v[32:35], v[0:15]
	v_add_u32_e32 v34, v66, v77
	ds_read_b64_tr_b16 v[32:33], v34
	ds_read_b64_tr_b16 v[34:35], v34 offset:2304
	ds_read_b128 v[56:59], v94
	s_waitcnt lgkmcnt(0)
	v_mfma_f32_32x32x16_bf16 v[16:31], v[56:59], v[32:35], v[16:31]
	ds_read_b128 v[56:59], v94 offset:8704
	s_waitcnt lgkmcnt(0)
	v_mfma_f32_32x32x16_bf16 v[0:15], v[56:59], v[32:35], v[0:15]
	v_add_u32_e32 v34, v66, v78
	ds_read_b64_tr_b16 v[32:33], v34
	ds_read_b64_tr_b16 v[34:35], v34 offset:2304
	ds_read_b128 v[56:59], v95
	s_waitcnt lgkmcnt(0)
	v_mfma_f32_32x32x16_bf16 v[16:31], v[56:59], v[32:35], v[16:31]
	ds_read_b128 v[56:59], v95 offset:8704
	s_waitcnt lgkmcnt(0)
	v_mfma_f32_32x32x16_bf16 v[0:15], v[56:59], v[32:35], v[0:15]
	ds_read_b64_tr_b16 v[32:33], v96
	ds_read_b64_tr_b16 v[34:35], v96 offset:2304
	ds_read_b128 v[56:59], v97
	s_waitcnt lgkmcnt(0)
	v_mfma_f32_32x32x16_bf16 v[16:31], v[56:59], v[32:35], v[16:31]
	ds_read_b128 v[56:59], v97 offset:8704
	s_waitcnt lgkmcnt(0)
	v_mfma_f32_32x32x16_bf16 v[0:15], v[56:59], v[32:35], v[0:15]
	ds_read_b64_tr_b16 v[32:33], v98
	ds_read_b64_tr_b16 v[34:35], v98 offset:2304
	ds_read_b128 v[56:59], v99
	s_waitcnt lgkmcnt(0)
	v_mfma_f32_32x32x16_bf16 v[16:31], v[56:59], v[32:35], v[16:31]
	ds_read_b128 v[56:59], v99 offset:8704
	s_waitcnt lgkmcnt(0)
	v_mfma_f32_32x32x16_bf16 v[0:15], v[56:59], v[32:35], v[0:15]
	ds_read_b64_tr_b16 v[32:33], v100
	ds_read_b64_tr_b16 v[34:35], v100 offset:2304
	ds_read_b128 v[56:59], v101
	s_waitcnt lgkmcnt(0)
	v_mfma_f32_32x32x16_bf16 v[16:31], v[56:59], v[32:35], v[16:31]
	ds_read_b128 v[56:59], v101 offset:8704
	s_waitcnt lgkmcnt(0)
	v_mfma_f32_32x32x16_bf16 v[0:15], v[56:59], v[32:35], v[0:15]
	ds_read_b64_tr_b16 v[32:33], v102
	ds_read_b64_tr_b16 v[34:35], v102 offset:2304
	ds_read_b128 v[56:59], v103
	s_waitcnt lgkmcnt(0)
	v_mfma_f32_32x32x16_bf16 v[16:31], v[56:59], v[32:35], v[16:31]
	ds_read_b128 v[56:59], v103 offset:8704
	s_waitcnt lgkmcnt(0)
	s_barrier
	v_mfma_f32_32x32x16_bf16 v[0:15], v[56:59], v[32:35], v[0:15]
	s_nop 7
	ds_write_b32 v104, v16
	ds_write_b32 v104, v17 offset:1040
	ds_write_b32 v104, v18 offset:2080
	ds_write_b32 v104, v19 offset:3120
	ds_write_b32 v104, v20 offset:8320
	ds_write_b32 v104, v21 offset:9360
	ds_write_b32 v104, v22 offset:10400
	ds_write_b32 v104, v23 offset:11440
	ds_write_b32 v104, v24 offset:16640
	ds_write_b32 v104, v25 offset:17680
	ds_write_b32 v104, v26 offset:18720
	ds_write_b32 v104, v27 offset:19760
	ds_write_b32 v104, v28 offset:24960
	ds_write_b32 v104, v29 offset:26000
	ds_write_b32 v104, v30 offset:27040
	ds_write_b32 v104, v31 offset:28080
	ds_write_b32 v104, v0 offset:33280
	ds_write_b32 v104, v1 offset:34320
	ds_write_b32 v104, v2 offset:35360
	ds_write_b32 v104, v3 offset:36400
	ds_write_b32 v104, v4 offset:41600
	ds_write_b32 v104, v5 offset:42640
	ds_write_b32 v104, v6 offset:43680
	ds_write_b32 v104, v7 offset:44720
	ds_write_b32 v104, v8 offset:49920
	ds_write_b32 v104, v9 offset:50960
	ds_write_b32 v104, v10 offset:52000
	ds_write_b32 v104, v11 offset:53040
	ds_write_b32 v104, v12 offset:58240
	ds_write_b32 v104, v13 offset:59280
	ds_write_b32 v104, v14 offset:60320
	ds_write_b32 v104, v15 offset:61360
	s_waitcnt lgkmcnt(0)
	s_barrier
	ds_read_b128 v[28:31], v105
	ds_read_b128 v[24:27], v105 offset:128
	ds_read_b128 v[20:23], v105 offset:256
	ds_read_b128 v[16:19], v105 offset:384
	ds_read_b128 v[12:15], v105 offset:512
	ds_read_b128 v[8:11], v105 offset:640
	s_waitcnt lgkmcnt(5)
	v_mov_b32_e32 v2, v29
	s_waitcnt lgkmcnt(4)
	v_mov_b32_e32 v3, v25
	v_mov_b32_e32 v0, v28
	v_mov_b32_e32 v1, v24
	v_pk_mul_f32 v[2:3], v[2:3], v[2:3]
	v_mov_b32_e32 v4, v31
	v_mov_b32_e32 v5, v27
	v_pk_fma_f32 v[0:1], v[0:1], v[0:1], v[2:3]
	v_mov_b32_e32 v2, v30
	v_mov_b32_e32 v3, v26
	v_pk_mul_f32 v[4:5], v[4:5], v[4:5]
	s_nop 0
	v_pk_fma_f32 v[2:3], v[2:3], v[2:3], v[4:5]
	s_waitcnt lgkmcnt(3)
	v_pk_mul_f32 v[4:5], v[20:21], v[20:21]
	v_pk_add_f32 v[0:1], v[0:1], v[2:3]
	v_pk_mul_f32 v[2:3], v[22:23], v[22:23]
	v_pk_add_f32 v[0:1], v[0:1], v[0:1] op_sel:[0,1] op_sel_hi:[1,0]
	v_pk_mov_b32 v[6:7], v[4:5], v[2:3] op_sel:[1,0]
	v_mov_b32_e32 v5, v3
	v_pk_add_f32 v[2:3], v[6:7], v[4:5]
	s_waitcnt lgkmcnt(1)
	v_mul_f32_e32 v4, v12, v12
	v_mul_f32_e32 v5, v13, v13
	v_pk_add_f32 v[2:3], v[2:3], v[2:3] op_sel:[0,1] op_sel_hi:[1,0]
	v_mov_b32_e32 v1, v4
	v_mov_b32_e32 v3, v5
	v_pk_add_f32 v[0:1], v[0:1], v[2:3]
	v_mul_f32_e32 v2, v17, v17
	v_mul_f32_e32 v4, v19, v19
	v_mul_f32_e32 v6, v14, v14
	v_mul_f32_e32 v7, v15, v15
	v_pk_fma_f32 v[2:3], v[16:17], v[16:17], v[2:3] op_sel_hi:[1,1,0]
	v_pk_fma_f32 v[4:5], v[18:19], v[18:19], v[4:5] op_sel_hi:[1,1,0]
	v_mov_b32_e32 v3, v6
	v_mov_b32_e32 v5, v7
	v_pk_add_f32 v[2:3], v[2:3], v[4:5]
	s_nop 0
	v_pk_add_f32 v[32:33], v[0:1], v[2:3]
	s_waitcnt lgkmcnt(0)
	v_pk_mul_f32 v[0:1], v[10:11], v[10:11]
	v_pk_mul_f32 v[2:3], v[8:9], v[8:9]
	v_pk_add_f32 v[32:33], v[32:33], v[32:33] op_sel:[0,1] op_sel_hi:[1,0]
	v_pk_mov_b32 v[4:5], v[2:3], v[0:1] op_sel:[1,0]
	v_mov_b32_e32 v3, v1
	v_pk_add_f32 v[34:35], v[4:5], v[2:3]
	ds_read_b128 v[4:7], v105 offset:768
	ds_read_b128 v[0:3], v105 offset:896
	v_pk_add_f32 v[34:35], v[34:35], v[34:35] op_sel:[0,1] op_sel_hi:[1,0]
	s_waitcnt lgkmcnt(0)
	v_mul_f32_e32 v53, v0, v0
	v_mul_f32_e32 v55, v1, v1
	v_mov_b32_e32 v33, v53
	v_mov_b32_e32 v35, v55
	v_pk_add_f32 v[32:33], v[32:33], v[34:35]
	v_mul_f32_e32 v34, v5, v5
	v_mul_f32_e32 v56, v2, v2
	v_pk_fma_f32 v[34:35], v[4:5], v[4:5], v[34:35] op_sel_hi:[1,1,0]
	v_mul_f32_e32 v58, v3, v3
	v_mov_b32_e32 v35, v56
	v_mul_f32_e32 v56, v7, v7
	v_pk_fma_f32 v[56:57], v[6:7], v[6:7], v[56:57] op_sel_hi:[1,1,0]
	s_nop 0
	v_mov_b32_e32 v57, v58
	v_pk_add_f32 v[34:35], v[34:35], v[56:57]
	s_nop 0
	v_pk_add_f32 v[32:33], v[32:33], v[34:35]
	v_and_b32_e32 v35, 64, v108
	v_xor_b32_e32 v34, 1, v108
	v_add_u32_e32 v35, 64, v35
	v_cmp_lt_i32_e32 vcc, v34, v35
	v_add_f32_e32 v33, v32, v33
	v_add_u32_e32 v32, s33, v67
	v_cndmask_b32_e32 v34, v108, v34, vcc
	v_lshlrev_b32_e32 v34, 2, v34
	ds_bpermute_b32 v34, v34, v33
	s_waitcnt lgkmcnt(0)
	v_add_f32_e32 v33, v33, v34
	v_xor_b32_e32 v34, 2, v108
	v_cmp_lt_i32_e32 vcc, v34, v35
	s_nop 1
	v_cndmask_b32_e32 v34, v108, v34, vcc
	v_lshlrev_b32_e32 v34, 2, v34
	ds_bpermute_b32 v34, v34, v33
	s_waitcnt lgkmcnt(0)
	v_add_f32_e32 v33, v33, v34
	v_xor_b32_e32 v34, 4, v108
	v_cmp_lt_i32_e32 vcc, v34, v35
	s_nop 1
	v_cndmask_b32_e32 v34, v108, v34, vcc
	v_lshlrev_b32_e32 v34, 2, v34
	ds_bpermute_b32 v34, v34, v33
	s_waitcnt lgkmcnt(0)
	v_add_f32_e32 v33, v33, v34
	v_fmamk_f32 v33, v33, 0x3b800000, v106
	v_cmp_gt_f32_e32 vcc, s97, v33
	v_mul_f32_e32 v34, 0x4f800000, v33
	s_nop 0
	v_cndmask_b32_e32 v33, v33, v34, vcc
	v_sqrt_f32_e32 v34, v33
	s_nop 0
	v_add_u32_e32 v35, -1, v34
	v_fma_f32 v53, -v35, v34, v33
	v_cmp_ge_f32_e64 s[48:49], 0, v53
	v_add_u32_e32 v53, 1, v34
	s_nop 0
	v_cndmask_b32_e64 v35, v34, v35, s[48:49]
	v_fma_f32 v34, -v53, v34, v33
	v_cmp_lt_f32_e64 s[48:49], 0, v34
	s_nop 1
	v_cndmask_b32_e64 v34, v35, v53, s[48:49]
	v_mul_f32_e32 v35, 0x37800000, v34
	v_cndmask_b32_e32 v34, v34, v35, vcc
	v_cmp_class_f32_e32 vcc, v33, v107
	s_nop 1
	v_cndmask_b32_e32 v33, v34, v33, vcc
	v_div_scale_f32 v34, s[48:49], v33, v33, 1.0
	v_rcp_f32_e32 v35, v34
	s_nop 0
	v_fma_f32 v53, -v34, v35, 1.0
	v_fmac_f32_e32 v35, v53, v35
	v_div_scale_f32 v53, vcc, 1.0, v33, 1.0
	v_mul_f32_e32 v55, v53, v35
	v_fma_f32 v56, -v34, v55, v53
	v_fmac_f32_e32 v55, v56, v35
	v_fma_f32 v34, -v34, v55, v53
	v_div_fmas_f32 v34, v34, v35, v55
	v_div_fixup_f32 v53, v34, v33, 1.0
	v_ashrrev_i32_e32 v33, 31, v32
	v_mov_b64_e32 v[34:35], s[60:61]
	v_mad_i64_i32 v[34:35], s[48:49], v32, s3, v[34:35]
	v_lshlrev_b64 v[32:33], 11, v[32:33]
	v_lshl_add_u64 v[34:35], v[34:35], 0, s[66:67]
	v_lshl_add_u64 v[32:33], s[64:65], 0, v[32:33]
	v_mov_b32_e32 v55, v37
	v_lshl_add_u64 v[58:59], v[32:33], 0, s[66:67]
	v_lshl_add_u64 v[32:33], v[34:35], 0, v[54:55]
	v_lshl_add_u64 v[56:57], v[32:33], 0, s[74:75]
	v_add_co_u32_e32 v32, vcc, s84, v32
	v_mul_f32_e32 v113, v28, v53
	s_nop 0
	v_addc_co_u32_e32 v33, vcc, 0, v33, vcc
	global_load_dwordx2 v[110:111], v[32:33], off
	s_nop 0
	global_load_dwordx4 v[32:35], v[40:41], off
	global_load_dwordx2 v[184:185], v[56:57], off offset:64
	global_load_dwordx4 v[188:191], v[40:41], off offset:128
	global_load_dwordx2 v[192:193], v[56:57], off offset:128
	global_load_dwordx4 v[196:199], v[40:41], off offset:256
	global_load_dwordx2 v[200:201], v[56:57], off offset:192
	global_load_dwordx4 v[204:207], v[40:41], off offset:384
	global_load_dwordx2 v[208:209], v[56:57], off offset:256
	global_load_dwordx4 v[212:215], v[40:41], off offset:512
	global_load_dwordx2 v[216:217], v[56:57], off offset:320
	global_load_dwordx4 v[220:223], v[40:41], off offset:640
	global_load_dwordx2 v[224:225], v[56:57], off offset:384
	global_load_dwordx4 v[228:231], v[40:41], off offset:768
	global_load_dwordx2 v[232:233], v[56:57], off offset:448
	global_load_dwordx4 v[236:239], v[40:41], off offset:896
	v_mul_f32_e32 v115, v30, v53
	v_mul_f32_e32 v117, v31, v53
	s_waitcnt vmcnt(14) lgkmcnt(0)
	v_lshlrev_b32_e32 v112, 16, v110
	v_mul_f32_e32 v28, 0xbfb8aa3b, v112
	v_exp_f32_e32 v28, v28
	v_and_b32_e32 v110, 0xffff0000, v110
	v_mov_b32_e32 v119, v32
	v_lshlrev_b32_e32 v114, 16, v111
	v_add_f32_e32 v28, 1.0, v28
	v_rcp_f32_e32 v118, v28
	v_mul_f32_e32 v28, 0xbfb8aa3b, v110
	v_exp_f32_e32 v28, v28
	v_and_b32_e32 v116, 0xffff0000, v111
	v_mul_f32_e32 v111, v29, v53
	v_pk_mul_f32 v[112:113], v[118:119], v[112:113]
	v_add_f32_e32 v28, 1.0, v28
	v_rcp_f32_e32 v32, v28
	v_mul_f32_e32 v109, v112, v113
	v_mul_f32_e32 v112, v26, v53
	v_pk_mul_f32 v[28:29], v[32:33], v[110:111]
	s_nop 0
	v_mul_f32_e32 v28, v28, v29
	v_cvt_pk_bf16_f32 v32, v109, v28
	v_mul_f32_e32 v28, 0xbfb8aa3b, v114
	v_exp_f32_e32 v28, v28
	v_mov_b32_e32 v29, v34
	v_mul_f32_e32 v110, v25, v53
	v_add_f32_e32 v28, 1.0, v28
	v_rcp_f32_e32 v28, v28
	s_nop 0
	v_pk_mul_f32 v[28:29], v[28:29], v[114:115]
	s_nop 0
	v_mul_f32_e32 v30, v28, v29
	v_mul_f32_e32 v28, 0xbfb8aa3b, v116
	v_exp_f32_e32 v28, v28
	s_nop 0
	v_add_f32_e32 v28, 1.0, v28
	v_rcp_f32_e32 v34, v28
	s_nop 0
	v_pk_mul_f32 v[28:29], v[34:35], v[116:117]
	s_nop 0
	v_mul_f32_e32 v28, v28, v29
	v_cvt_pk_bf16_f32 v33, v30, v28
	v_lshl_add_u64 v[28:29], v[58:59], 0, v[54:55]
	global_store_dwordx2 v[28:29], v[32:33], off
	s_nop 0
	v_mul_f32_e32 v58, v24, v53
	s_waitcnt vmcnt(13) lgkmcnt(0)
	v_mov_b64_e32 v[34:35], v[184:185]
	v_mov_b64_e32 v[30:31], v[188:189]
	v_mov_b64_e32 v[32:33], v[190:191]
	v_lshlrev_b32_e32 v59, 16, v34
	v_mul_f32_e32 v24, 0xbfb8aa3b, v59
	v_exp_f32_e32 v24, v24
	v_and_b32_e32 v111, 0xffff0000, v34
	v_lshlrev_b32_e32 v113, 16, v35
	v_and_b32_e32 v35, 0xffff0000, v35
	v_add_f32_e32 v24, 1.0, v24
	v_rcp_f32_e32 v115, v24
	v_mul_f32_e32 v24, 0xbfb8aa3b, v111
	v_exp_f32_e32 v24, v24
	v_mul_f32_e32 v26, 0xbfb8aa3b, v35
	v_exp_f32_e32 v26, v26
	v_mov_b32_e32 v114, v30
	v_add_f32_e32 v24, 1.0, v24
	v_rcp_f32_e32 v25, v24
	v_mov_b32_e32 v24, v31
	v_add_f32_e32 v26, 1.0, v26
	v_pk_mul_f32 v[58:59], v[114:115], v[58:59]
	v_pk_mul_f32 v[24:25], v[24:25], v[110:111]
	v_mul_f32_e32 v34, v27, v53
	v_mul_f32_e32 v24, v24, v25
	v_mul_f32_e32 v25, 0xbfb8aa3b, v113
	v_exp_f32_e32 v25, v25
	v_rcp_f32_e32 v27, v26
	v_mul_f32_e32 v30, v58, v59
	v_cvt_pk_bf16_f32 v24, v30, v24
	v_add_f32_e32 v25, 1.0, v25
	v_rcp_f32_e32 v31, v25
	v_mov_b32_e32 v30, v32
	v_mov_b32_e32 v26, v33
	v_pk_mul_f32 v[26:27], v[26:27], v[34:35]
	v_pk_mul_f32 v[30:31], v[30:31], v[112:113]
	v_mul_f32_e32 v26, v26, v27
	v_mul_f32_e32 v25, v30, v31
	v_cvt_pk_bf16_f32 v25, v25, v26
	global_store_dwordx2 v[28:29], v[24:25], off offset:64
	s_nop 0
	v_mul_f32_e32 v110, v20, v53
	s_waitcnt vmcnt(12) lgkmcnt(0)
	v_mov_b64_e32 v[30:31], v[192:193]
	v_mov_b64_e32 v[24:25], v[196:197]
	v_mov_b64_e32 v[26:27], v[198:199]
	v_lshlrev_b32_e32 v33, 16, v30
	v_mul_f32_e32 v20, 0xbfb8aa3b, v33
	v_exp_f32_e32 v20, v20
	v_and_b32_e32 v35, 0xffff0000, v30
	v_mov_b32_e32 v32, v24
	v_mov_b32_e32 v34, v25
	v_add_f32_e32 v20, 1.0, v20
	v_rcp_f32_e32 v111, v20
	v_mul_f32_e32 v20, v21, v53
	v_mul_f32_e32 v21, 0xbfb8aa3b, v35
	v_exp_f32_e32 v21, v21
	v_lshlrev_b32_e32 v59, 16, v31
	v_pk_mul_f32 v[32:33], v[110:111], v[32:33]
	v_and_b32_e32 v31, 0xffff0000, v31
	v_add_f32_e32 v21, 1.0, v21
	v_rcp_f32_e32 v21, v21
	v_mul_f32_e32 v24, v32, v33
	v_mov_b32_e32 v58, v26
	v_mov_b32_e32 v30, v27
	v_pk_mul_f32 v[20:21], v[20:21], v[34:35]
	v_mul_f32_e32 v34, v16, v53
	v_mul_f32_e32 v20, v20, v21
	v_mul_f32_e32 v21, 0xbfb8aa3b, v59
	v_cvt_pk_bf16_f32 v20, v24, v20
	v_mul_f32_e32 v24, v22, v53
	v_exp_f32_e32 v21, v21
	v_mul_f32_e32 v22, v23, v53
	v_mul_f32_e32 v23, 0xbfb8aa3b, v31
	v_exp_f32_e32 v23, v23
	v_add_f32_e32 v21, 1.0, v21
	v_rcp_f32_e32 v25, v21
	v_add_f32_e32 v23, 1.0, v23
	v_rcp_f32_e32 v23, v23
	v_pk_mul_f32 v[24:25], v[24:25], v[58:59]
	v_pk_mul_f32 v[22:23], v[22:23], v[30:31]
	v_mul_f32_e32 v21, v24, v25
	v_mul_f32_e32 v22, v22, v23
	v_cvt_pk_bf16_f32 v21, v21, v22
	global_store_dwordx2 v[28:29], v[20:21], off offset:128
	s_nop 0
	s_waitcnt vmcnt(11) lgkmcnt(0)
	v_mov_b64_e32 v[24:25], v[200:201]
	v_mov_b64_e32 v[20:21], v[204:205]
	v_mov_b64_e32 v[22:23], v[206:207]
	v_lshlrev_b32_e32 v27, 16, v24
	v_mul_f32_e32 v16, 0xbfb8aa3b, v27
	v_exp_f32_e32 v16, v16
	v_and_b32_e32 v31, 0xffff0000, v24
	v_mov_b32_e32 v26, v20
	v_mov_b32_e32 v30, v21
	v_add_f32_e32 v16, 1.0, v16
	v_rcp_f32_e32 v35, v16
	v_mul_f32_e32 v16, v17, v53
	v_mul_f32_e32 v17, 0xbfb8aa3b, v31
	v_exp_f32_e32 v17, v17
	v_lshlrev_b32_e32 v33, 16, v25
	v_pk_mul_f32 v[26:27], v[34:35], v[26:27]
	v_and_b32_e32 v25, 0xffff0000, v25
	v_add_f32_e32 v17, 1.0, v17
	v_rcp_f32_e32 v17, v17
	v_mul_f32_e32 v20, v26, v27
	v_mov_b32_e32 v32, v22
	v_mov_b32_e32 v24, v23
	v_pk_mul_f32 v[16:17], v[16:17], v[30:31]
	v_mul_f32_e32 v30, v12, v53
	v_mul_f32_e32 v16, v16, v17
	v_mul_f32_e32 v17, 0xbfb8aa3b, v33
	v_cvt_pk_bf16_f32 v16, v20, v16
	v_mul_f32_e32 v20, v18, v53
	v_exp_f32_e32 v17, v17
	v_mul_f32_e32 v18, v19, v53
	v_mul_f32_e32 v19, 0xbfb8aa3b, v25
	v_exp_f32_e32 v19, v19
	v_add_f32_e32 v17, 1.0, v17
	v_rcp_f32_e32 v21, v17
	v_add_f32_e32 v19, 1.0, v19
	v_rcp_f32_e32 v19, v19
	v_pk_mul_f32 v[20:21], v[20:21], v[32:33]
	v_pk_mul_f32 v[18:19], v[18:19], v[24:25]
	v_mul_f32_e32 v17, v20, v21
	v_mul_f32_e32 v18, v18, v19
	v_cvt_pk_bf16_f32 v17, v17, v18
	global_store_dwordx2 v[28:29], v[16:17], off offset:192
	s_nop 0
	s_waitcnt vmcnt(10) lgkmcnt(0)
	v_mov_b64_e32 v[20:21], v[208:209]
	v_mov_b64_e32 v[16:17], v[212:213]
	v_mov_b64_e32 v[18:19], v[214:215]
	v_lshlrev_b32_e32 v23, 16, v20
	v_mul_f32_e32 v12, 0xbfb8aa3b, v23
	v_exp_f32_e32 v12, v12
	v_and_b32_e32 v25, 0xffff0000, v20
	v_mov_b32_e32 v22, v16
	v_mov_b32_e32 v24, v17
	v_add_f32_e32 v12, 1.0, v12
	v_rcp_f32_e32 v31, v12
	v_mul_f32_e32 v12, v13, v53
	v_mul_f32_e32 v13, 0xbfb8aa3b, v25
	v_exp_f32_e32 v13, v13
	v_lshlrev_b32_e32 v27, 16, v21
	v_pk_mul_f32 v[22:23], v[30:31], v[22:23]
	v_and_b32_e32 v21, 0xffff0000, v21
	v_add_f32_e32 v13, 1.0, v13
	v_rcp_f32_e32 v13, v13
	v_mul_f32_e32 v16, v22, v23
	v_mov_b32_e32 v26, v18
	v_mov_b32_e32 v20, v19
	v_pk_mul_f32 v[12:13], v[12:13], v[24:25]
	v_mul_f32_e32 v24, v8, v53
	v_mul_f32_e32 v12, v12, v13
	v_mul_f32_e32 v13, 0xbfb8aa3b, v27
	v_cvt_pk_bf16_f32 v12, v16, v12
	v_mul_f32_e32 v16, v14, v53
	v_exp_f32_e32 v13, v13
	v_mul_f32_e32 v14, v15, v53
	v_mul_f32_e32 v15, 0xbfb8aa3b, v21
	v_exp_f32_e32 v15, v15
	v_add_f32_e32 v13, 1.0, v13
	v_rcp_f32_e32 v17, v13
	v_add_f32_e32 v15, 1.0, v15
	v_rcp_f32_e32 v15, v15
	v_pk_mul_f32 v[16:17], v[16:17], v[26:27]
	v_pk_mul_f32 v[14:15], v[14:15], v[20:21]
	v_mul_f32_e32 v13, v16, v17
	v_mul_f32_e32 v14, v14, v15
	v_cvt_pk_bf16_f32 v13, v13, v14
	global_store_dwordx2 v[28:29], v[12:13], off offset:256
	s_nop 0
	s_waitcnt vmcnt(9) lgkmcnt(0)
	v_mov_b64_e32 v[16:17], v[216:217]
	v_mov_b64_e32 v[12:13], v[220:221]
	v_mov_b64_e32 v[14:15], v[222:223]
	v_lshlrev_b32_e32 v19, 16, v16
	v_mul_f32_e32 v8, 0xbfb8aa3b, v19
	v_exp_f32_e32 v8, v8
	v_and_b32_e32 v21, 0xffff0000, v16
	v_mov_b32_e32 v18, v12
	v_mov_b32_e32 v20, v13
	v_add_f32_e32 v8, 1.0, v8
	v_rcp_f32_e32 v25, v8
	v_mul_f32_e32 v8, v9, v53
	v_mul_f32_e32 v9, 0xbfb8aa3b, v21
	v_exp_f32_e32 v9, v9
	v_lshlrev_b32_e32 v23, 16, v17
	v_pk_mul_f32 v[18:19], v[24:25], v[18:19]
	v_and_b32_e32 v17, 0xffff0000, v17
	v_add_f32_e32 v9, 1.0, v9
	v_rcp_f32_e32 v9, v9
	v_mul_f32_e32 v12, v18, v19
	v_mov_b32_e32 v22, v14
	v_mov_b32_e32 v16, v15
	v_pk_mul_f32 v[8:9], v[8:9], v[20:21]
	v_mul_f32_e32 v20, v4, v53
	v_mul_f32_e32 v8, v8, v9
	v_mul_f32_e32 v9, 0xbfb8aa3b, v23
	v_cvt_pk_bf16_f32 v8, v12, v8
	v_mul_f32_e32 v12, v10, v53
	v_exp_f32_e32 v9, v9
	v_mul_f32_e32 v10, v11, v53
	v_mul_f32_e32 v11, 0xbfb8aa3b, v17
	v_exp_f32_e32 v11, v11
	v_add_f32_e32 v9, 1.0, v9
	v_rcp_f32_e32 v13, v9
	v_add_f32_e32 v11, 1.0, v11
	v_rcp_f32_e32 v11, v11
	v_pk_mul_f32 v[12:13], v[12:13], v[22:23]
	v_pk_mul_f32 v[10:11], v[10:11], v[16:17]
	v_mul_f32_e32 v9, v12, v13
	v_mul_f32_e32 v10, v10, v11
	v_cvt_pk_bf16_f32 v9, v9, v10
	global_store_dwordx2 v[28:29], v[8:9], off offset:320
	s_nop 0
	s_waitcnt vmcnt(8) lgkmcnt(0)
	v_mov_b64_e32 v[12:13], v[224:225]
	v_mov_b64_e32 v[8:9], v[228:229]
	v_mov_b64_e32 v[10:11], v[230:231]
	v_lshlrev_b32_e32 v15, 16, v12
	v_mul_f32_e32 v4, 0xbfb8aa3b, v15
	v_exp_f32_e32 v4, v4
	v_and_b32_e32 v17, 0xffff0000, v12
	v_mov_b32_e32 v14, v8
	v_mov_b32_e32 v16, v9
	v_add_f32_e32 v4, 1.0, v4
	v_rcp_f32_e32 v21, v4
	v_mul_f32_e32 v4, v5, v53
	v_mul_f32_e32 v5, 0xbfb8aa3b, v17
	v_exp_f32_e32 v5, v5
	v_lshlrev_b32_e32 v19, 16, v13
	v_pk_mul_f32 v[14:15], v[20:21], v[14:15]
	v_and_b32_e32 v13, 0xffff0000, v13
	v_add_f32_e32 v5, 1.0, v5
	v_rcp_f32_e32 v5, v5
	v_mul_f32_e32 v8, v14, v15
	v_mov_b32_e32 v18, v10
	v_mov_b32_e32 v12, v11
	v_pk_mul_f32 v[4:5], v[4:5], v[16:17]
	v_mul_f32_e32 v16, v0, v53
	v_mul_f32_e32 v4, v4, v5
	v_mul_f32_e32 v5, 0xbfb8aa3b, v19
	v_cvt_pk_bf16_f32 v4, v8, v4
	v_mul_f32_e32 v8, v6, v53
	v_exp_f32_e32 v5, v5
	v_mul_f32_e32 v6, v7, v53
	v_mul_f32_e32 v7, 0xbfb8aa3b, v13
	v_exp_f32_e32 v7, v7
	v_add_f32_e32 v5, 1.0, v5
	v_rcp_f32_e32 v9, v5
	v_add_f32_e32 v7, 1.0, v7
	v_rcp_f32_e32 v7, v7
	v_pk_mul_f32 v[8:9], v[8:9], v[18:19]
	v_pk_mul_f32 v[6:7], v[6:7], v[12:13]
	v_mul_f32_e32 v5, v8, v9
	v_mul_f32_e32 v6, v6, v7
	v_cvt_pk_bf16_f32 v5, v5, v6
	global_store_dwordx2 v[28:29], v[4:5], off offset:384
	s_nop 0
	s_waitcnt vmcnt(7) lgkmcnt(0)
	v_mov_b64_e32 v[8:9], v[232:233]
	v_mov_b64_e32 v[4:5], v[236:237]
	v_mov_b64_e32 v[6:7], v[238:239]
	v_lshlrev_b32_e32 v11, 16, v8
	v_mul_f32_e32 v0, 0xbfb8aa3b, v11
	v_exp_f32_e32 v0, v0
	v_and_b32_e32 v13, 0xffff0000, v8
	v_mov_b32_e32 v10, v4
	v_mov_b32_e32 v12, v5
	v_add_f32_e32 v0, 1.0, v0
	v_rcp_f32_e32 v17, v0
	v_mul_f32_e32 v0, v1, v53
	v_mul_f32_e32 v1, 0xbfb8aa3b, v13
	v_exp_f32_e32 v1, v1
	v_lshlrev_b32_e32 v15, 16, v9
	v_pk_mul_f32 v[10:11], v[16:17], v[10:11]
	v_and_b32_e32 v9, 0xffff0000, v9
	v_add_f32_e32 v1, 1.0, v1
	v_rcp_f32_e32 v1, v1
	v_mul_f32_e32 v4, v10, v11
	v_mov_b32_e32 v14, v6
	v_mov_b32_e32 v8, v7
	v_pk_mul_f32 v[0:1], v[0:1], v[12:13]
	s_nop 0
	v_mul_f32_e32 v0, v0, v1
	v_mul_f32_e32 v1, 0xbfb8aa3b, v15
	v_cvt_pk_bf16_f32 v0, v4, v0
	v_mul_f32_e32 v4, v2, v53
	v_exp_f32_e32 v1, v1
	v_mul_f32_e32 v2, v3, v53
	v_mul_f32_e32 v3, 0xbfb8aa3b, v9
	v_exp_f32_e32 v3, v3
	v_add_f32_e32 v1, 1.0, v1
	v_rcp_f32_e32 v5, v1
	v_add_f32_e32 v3, 1.0, v3
	v_rcp_f32_e32 v3, v3
	v_pk_mul_f32 v[4:5], v[4:5], v[14:15]
	v_pk_mul_f32 v[2:3], v[2:3], v[8:9]
	v_mul_f32_e32 v1, v4, v5
	v_mul_f32_e32 v2, v2, v3
	v_cvt_pk_bf16_f32 v1, v1, v2
	global_store_dwordx2 v[28:29], v[0:1], off offset:448
	s_waitcnt lgkmcnt(0)
	s_barrier
	s_cbranch_scc0 .LBB0_1072

.LBB0_1061:
	v_add_u32_e32 v2, s33, v60
	v_ashrrev_i32_e32 v3, 31, v2
	s_and_b32 s48, s48, 1
	v_lshlrev_b64 v[0:1], 10, v[2:3]
	v_lshl_add_u64 v[0:1], s[62:63], 0, v[0:1]
	s_lshl_b32 s66, s48, 8
	v_lshl_add_u64 v[0:1], v[0:1], 0, s[66:67]
	v_lshl_add_u64 v[4:5], v[0:1], 0, v[36:37]
	flat_load_ushort v6, v[4:5]
	v_mov_b64_e32 v[0:1], s[60:61]
	v_mad_i64_i32 v[2:3], vcc, v2, s3, v[0:1]
	v_lshl_add_u64 v[2:3], v[2:3], 0, s[66:67]
	v_lshl_add_u64 v[2:3], v[2:3], 0, v[36:37]
	v_add_co_u32_e32 v12, vcc, s84, v2
	s_movk_i32 s49, 0x4000
	s_nop 0
	v_addc_co_u32_e32 v13, vcc, 0, v3, vcc
	v_add_u32_e32 v53, s33, v68
	s_lshl_b32 s48, s48, 9
	v_add_u32_e32 v124, v62, v71
	s_waitcnt vmcnt(0) lgkmcnt(0)
	v_cvt_f32_f16_e32 v7, v6
	v_mov_b32_e32 v6, 0
	v_add_f32_e32 v8, 0, v7
	flat_load_ushort v10, v[2:3]
	flat_load_ushort v11, v[2:3] offset:1024
	flat_load_ushort v7, v[4:5] offset:1024
	flat_load_ushort v14, v[12:13] offset:2048
	flat_load_ushort v15, v[12:13] offset:3072
	flat_load_ushort v9, v[4:5] offset:2048
	v_add_co_u32_e32 v12, vcc, s85, v2
	s_waitcnt vmcnt(0) lgkmcnt(0)
	v_cvt_f32_f16_e32 v7, v7
	v_addc_co_u32_e32 v13, vcc, 0, v3, vcc
	v_add_co_u32_e32 v16, vcc, s49, v2
	s_movk_i32 s49, 0x6000
	s_nop 0
	v_addc_co_u32_e32 v17, vcc, 0, v3, vcc
	v_add_co_u32_e32 v20, vcc, s84, v4
	flat_load_ushort v18, v[12:13]
	flat_load_ushort v19, v[12:13] offset:1024
	s_nop 0
	flat_load_ushort v12, v[4:5] offset:3072
	v_addc_co_u32_e32 v21, vcc, 0, v5, vcc
	flat_load_ushort v23, v[16:17] offset:2048
	flat_load_ushort v24, v[16:17] offset:3072
	v_add_co_u32_e32 v16, vcc, s49, v2
	s_movk_i32 s49, 0x7000
	s_nop 0
	v_addc_co_u32_e32 v17, vcc, 0, v3, vcc
	v_add_co_u32_e32 v30, vcc, s49, v2
	s_mov_b32 s49, 0x9000
	s_nop 0
	v_addc_co_u32_e32 v31, vcc, 0, v3, vcc
	v_add_co_u32_e32 v34, vcc, s49, v2
	s_mov_b32 s49, 0xa000
	s_nop 0
	v_addc_co_u32_e32 v35, vcc, 0, v3, vcc
	flat_load_ushort v13, v[20:21]
	v_add_co_u32_e32 v56, vcc, s49, v2
	flat_load_ushort v27, v[16:17]
	flat_load_ushort v28, v[16:17] offset:1024
	s_nop 0
	flat_load_ushort v16, v[20:21] offset:1024
	v_addc_co_u32_e32 v57, vcc, 0, v3, vcc
	s_movk_i32 s49, 0x2000
	flat_load_ushort v29, v[30:31] offset:2048
	s_nop 0
	flat_load_ushort v30, v[30:31] offset:3072
	s_nop 0
	flat_load_ushort v17, v[20:21] offset:2048
	v_add_co_u32_e32 v112, vcc, s49, v4
	flat_load_ushort v33, v[34:35]
	s_nop 0
	flat_load_ushort v34, v[34:35] offset:1024
	s_nop 0
	flat_load_ushort v20, v[20:21] offset:3072
	v_addc_co_u32_e32 v113, vcc, 0, v5, vcc
	flat_load_ushort v35, v[56:57] offset:2048
	flat_load_ushort v55, v[56:57] offset:3072
	flat_load_ushort v21, v[112:113]
	v_cvt_f32_f16_e32 v9, v9
	v_add_f32_e32 v7, v8, v7
	s_mov_b32 s49, 0xc000
	v_add_co_u32_e32 v58, vcc, s49, v2
	v_add_f32_e32 v9, v7, v9
	s_nop 0
	v_addc_co_u32_e32 v59, vcc, 0, v3, vcc
	v_add_co_u32_e32 v110, vcc, s86, v2
	s_mov_b32 s49, s67
	s_nop 0
	v_addc_co_u32_e32 v111, vcc, 0, v3, vcc
	s_waitcnt vmcnt(0) lgkmcnt(0)
	v_cvt_f32_f16_e32 v12, v12
	v_add_f32_e32 v12, v9, v12
	v_cvt_f32_f16_e32 v13, v13
	v_cvt_f32_f16_e32 v16, v16
	v_add_f32_e32 v13, v12, v13
	v_cvt_f32_f16_e32 v17, v17
	v_add_f32_e32 v16, v13, v16
	v_cvt_f32_f16_e32 v20, v20
	v_add_f32_e32 v17, v16, v17
	v_cvt_f32_f16_e32 v21, v21
	v_add_f32_e32 v20, v17, v20
	v_add_f32_e32 v22, v20, v21
	flat_load_ushort v56, v[58:59]
	flat_load_ushort v57, v[58:59] offset:1024
	flat_load_ushort v21, v[112:113] offset:1024
	s_nop 0
	flat_load_ushort v58, v[110:111] offset:2048
	flat_load_ushort v59, v[110:111] offset:3072
	flat_load_ushort v25, v[112:113] offset:2048
	v_add_co_u32_e32 v110, vcc, s87, v2
	s_waitcnt vmcnt(0) lgkmcnt(0)
	v_cvt_f32_f16_e32 v21, v21
	v_addc_co_u32_e32 v111, vcc, 0, v3, vcc
	flat_load_ushort v109, v[110:111]
	s_nop 0
	flat_load_ushort v110, v[110:111] offset:1024
	s_nop 0
	flat_load_ushort v26, v[112:113] offset:3072
	v_add_co_u32_e32 v112, vcc, s88, v2
	v_cvt_f32_f16_e32 v25, v25
	s_nop 0
	v_addc_co_u32_e32 v113, vcc, 0, v3, vcc
	v_add_co_u32_e32 v120, vcc, s85, v4
	flat_load_ushort v111, v[112:113] offset:2048
	s_nop 0
	flat_load_ushort v112, v[112:113] offset:3072
	v_addc_co_u32_e32 v121, vcc, 0, v5, vcc
	v_add_co_u32_e32 v114, vcc, s89, v2
	flat_load_ushort v4, v[120:121]
	s_nop 0
	v_addc_co_u32_e32 v115, vcc, 0, v3, vcc
	v_add_co_u32_e32 v116, vcc, s90, v2
	flat_load_ushort v113, v[114:115]
	s_nop 0
	flat_load_ushort v114, v[114:115] offset:1024
	s_nop 0
	flat_load_ushort v5, v[120:121] offset:1024
	v_addc_co_u32_e32 v117, vcc, 0, v3, vcc
	v_add_co_u32_e32 v118, vcc, s91, v2
	flat_load_ushort v115, v[116:117] offset:2048
	s_nop 0
	flat_load_ushort v116, v[116:117] offset:3072
	s_nop 0
	flat_load_ushort v31, v[120:121] offset:2048
	v_addc_co_u32_e32 v119, vcc, 0, v3, vcc
	flat_load_ushort v117, v[118:119]
	s_nop 0
	flat_load_ushort v118, v[118:119] offset:1024
	s_nop 0
	flat_load_ushort v32, v[120:121] offset:3072
	v_add_f32_e32 v21, v22, v21
	v_add_f32_e32 v25, v21, v25
	v_add_co_u32_e32 v120, vcc, s92, v2
	v_add_u32_e32 v119, v62, v69
	s_nop 0
	v_addc_co_u32_e32 v121, vcc, 0, v3, vcc
	flat_load_ushort v2, v[120:121] offset:2048
	flat_load_ushort v3, v[120:121] offset:3072
	v_mad_i64_i32 v[120:121], vcc, v53, s3, v[0:1]
	v_lshl_add_u64 v[120:121], v[120:121], 0, s[48:49]
	v_mov_b32_e32 v53, v37
	v_lshl_add_u64 v[120:121], v[120:121], 0, v[52:53]
	s_waitcnt vmcnt(0) lgkmcnt(0)
	v_cvt_f32_f16_e32 v26, v26
	v_add_f32_e32 v26, v25, v26
	v_cvt_f32_f16_e32 v4, v4
	v_add_f32_e32 v4, v26, v4
	v_cvt_f32_f16_e32 v5, v5
	v_add_f32_e32 v5, v4, v5
	v_cvt_f32_f16_e32 v31, v31
	v_cvt_f32_f16_e32 v32, v32
	v_add_f32_e32 v31, v5, v31
	v_add_f32_e32 v32, v31, v32
	ds_write_b32 v61, v32
	global_load_dwordx4 v[184:187], v[120:121], off offset:2048
	v_mov_b32_e32 v232, v119
	v_add_u32_e32 v120, s33, v70
	v_mad_i64_i32 v[120:121], vcc, v120, s3, v[0:1]
	v_lshl_add_u64 v[120:121], v[120:121], 0, s[48:49]
	v_lshl_add_u64 v[120:121], v[120:121], 0, v[52:53]
	global_load_dwordx4 v[188:191], v[120:121], off offset:2048
	v_mov_b32_e32 v233, v124
	v_add_u32_e32 v120, s33, v72
	v_mad_i64_i32 v[120:121], vcc, v120, s3, v[0:1]
	v_lshl_add_u64 v[120:121], v[120:121], 0, s[48:49]
	v_lshl_add_u64 v[120:121], v[120:121], 0, v[52:53]
	global_load_dwordx4 v[192:195], v[120:121], off offset:2048
	v_mov_b32_e32 v234, v119
	v_add_u32_e32 v119, s33, v73
	v_mad_i64_i32 v[0:1], vcc, v119, s3, v[0:1]
	v_lshl_add_u64 v[0:1], v[0:1], 0, s[48:49]
	v_lshl_add_u64 v[0:1], v[0:1], 0, v[52:53]
	global_load_dwordx4 v[196:199], v[0:1], off offset:2048
	v_add_u32_e32 v0, v62, v74
	v_add_u32_e32 v53, v63, v69
	v_add_u32_e32 v119, v63, v71
	v_mov_b32_e32 v235, v0
	v_lshl_add_u64 v[0:1], v[44:45], 0, v[38:39]
	v_add_co_u32_e32 v120, vcc, s93, v0
	s_nop 1
	v_addc_co_u32_e32 v121, vcc, 0, v1, vcc
	global_load_dwordx4 v[200:203], v[120:121], off
	v_mov_b32_e32 v236, v53
	v_lshl_add_u64 v[120:121], v[50:51], 0, v[38:39]
	global_load_dwordx4 v[204:207], v[120:121], off
	v_mov_b32_e32 v237, v119
	v_add_co_u32_e32 v120, vcc, s94, v0
	v_add_u32_e32 v119, v63, v74
	s_nop 0
	v_addc_co_u32_e32 v121, vcc, 0, v1, vcc
	global_load_dwordx4 v[208:211], v[120:121], off
	v_mov_b32_e32 v238, v53
	v_lshl_add_u64 v[120:121], v[48:49], 0, v[38:39]
	global_load_dwordx4 v[212:215], v[120:121], off
	v_mov_b32_e32 v239, v119
	v_add_co_u32_e32 v120, vcc, s95, v0
	s_nop 1
	v_addc_co_u32_e32 v121, vcc, 0, v1, vcc
	global_load_dwordx4 v[216:219], v[120:121], off
	v_add_co_u32_e32 v0, vcc, 0x9c0c000, v0
	v_mov_b32_e32 v240, v53
	v_lshl_add_u64 v[120:121], v[46:47], 0, v[38:39]
	global_load_dwordx4 v[220:223], v[120:121], off
	v_addc_co_u32_e32 v1, vcc, 0, v1, vcc
	v_mov_b32_e32 v241, v79
	global_load_dwordx4 v[224:227], v[0:1], off
	v_lshl_add_u64 v[0:1], v[42:43], 0, v[38:39]
	v_mov_b32_e32 v242, v53
	global_load_dwordx4 v[228:231], v[0:1], off
	v_mov_b32_e32 v243, v80
	s_waitcnt vmcnt(0)
	ds_write_b128 v232, v[184:187] offset:34816
	ds_write_b128 v233, v[188:191] offset:34816
	ds_write_b128 v234, v[192:195] offset:53248
	ds_write_b128 v235, v[196:199] offset:34816
	ds_write_b128 v236, v[200:203]
	ds_write_b128 v237, v[204:207]
	ds_write_b128 v238, v[208:211] offset:18432
	ds_write_b128 v239, v[212:215]
	ds_write_b128 v240, v[216:219] offset:36864
	ds_write_b128 v241, v[220:223]
	ds_write_b128 v242, v[224:227] offset:55296
	ds_write_b128 v243, v[228:231]
	s_waitcnt lgkmcnt(0)
	s_barrier
	s_and_saveexec_b64 s[48:49], s[6:7]
	s_cbranch_execnz .LBB0_1069
	s_or_b64 exec, exec, s[48:49]
	s_and_saveexec_b64 s[48:49], s[8:9]
	s_cbranch_execnz .LBB0_1070

.LBB0_1126:
	s_and_b32 s16, s16, 1
	v_add_u32_e32 v0, s48, v78
	s_or_b32 s22, s16, 2
	v_ashrrev_i32_e32 v1, 31, v0
	v_lshlrev_b64 v[2:3], 10, v[0:1]
	s_lshl_b32 s16, s22, 8
	v_mad_i64_i32 v[0:1], s[60:61], v0, s3, v[74:75]
	v_lshl_add_u64 v[0:1], v[0:1], 0, s[16:17]
	v_lshl_add_u64 v[4:5], v[0:1], 0, v[64:65]
	v_add_co_u32_e32 v0, vcc, s28, v4
	v_lshl_add_u64 v[2:3], s[14:15], 0, v[2:3]
	s_nop 0
	v_addc_co_u32_e32 v1, vcc, 0, v5, vcc
	v_add_co_u32_e32 v6, vcc, s29, v4
	v_lshl_add_u64 v[2:3], v[2:3], 0, s[16:17]
	s_nop 0
	v_addc_co_u32_e32 v7, vcc, 0, v5, vcc
	v_add_co_u32_e32 v8, vcc, s30, v4
	v_lshl_add_u64 v[2:3], v[2:3], 0, v[64:65]
	s_nop 0
	v_addc_co_u32_e32 v9, vcc, 0, v5, vcc
	flat_load_ushort v12, v[2:3]
	flat_load_ushort v13, v[2:3] offset:1024
	flat_load_ushort v14, v[0:1] offset:3072
	flat_load_ushort v15, v[2:3] offset:2048
	flat_load_ushort v16, v[6:7] offset:1024
	flat_load_ushort v17, v[8:9] offset:3072
	flat_load_ushort v18, v[2:3] offset:3072
	v_add_co_u32_e32 v0, vcc, s28, v2
	s_lshl_b32 s16, s22, 9
	s_nop 0
	v_addc_co_u32_e32 v1, vcc, 0, v3, vcc
	v_add_co_u32_e32 v6, vcc, s33, v4
	s_nop 1
	v_addc_co_u32_e32 v7, vcc, 0, v5, vcc
	v_add_co_u32_e32 v8, vcc, s34, v4
	s_nop 1
	v_addc_co_u32_e32 v9, vcc, 0, v5, vcc
	v_add_co_u32_e32 v10, vcc, s35, v4
	s_nop 1
	v_addc_co_u32_e32 v11, vcc, 0, v5, vcc
	flat_load_ushort v19, v[0:1]
	flat_load_ushort v20, v[0:1] offset:1024
	flat_load_ushort v21, v[6:7] offset:3072
	flat_load_ushort v22, v[0:1] offset:2048
	flat_load_ushort v23, v[8:9] offset:1024
	flat_load_ushort v24, v[10:11] offset:3072
	flat_load_ushort v25, v[0:1] offset:3072
	v_add_co_u32_e32 v0, vcc, s36, v2
	s_waitcnt vmcnt(0) lgkmcnt(0)
	v_lshlrev_b32_e32 v21, 16, v21
	v_addc_co_u32_e32 v1, vcc, 0, v3, vcc
	v_add_co_u32_e32 v6, vcc, s38, v4
	v_lshlrev_b32_e32 v23, 16, v23
	s_nop 0
	v_addc_co_u32_e32 v7, vcc, 0, v5, vcc
	v_add_co_u32_e32 v8, vcc, s39, v4
	v_lshlrev_b32_e32 v24, 16, v24
	s_nop 0
	v_addc_co_u32_e32 v9, vcc, 0, v5, vcc
	v_add_co_u32_e32 v10, vcc, s40, v4
	s_nop 1
	v_addc_co_u32_e32 v11, vcc, 0, v5, vcc
	flat_load_ushort v26, v[0:1]
	flat_load_ushort v27, v[0:1] offset:1024
	flat_load_ushort v28, v[6:7] offset:3072
	flat_load_ushort v29, v[0:1] offset:2048
	flat_load_ushort v30, v[8:9] offset:1024
	s_nop 0
	flat_load_ushort v10, v[10:11] offset:3072
	s_nop 0
	flat_load_ushort v11, v[0:1] offset:3072
	v_add_co_u32_e32 v0, vcc, s29, v2
	s_waitcnt vmcnt(0) lgkmcnt(0)
	v_lshlrev_b32_e32 v28, 16, v28
	v_addc_co_u32_e32 v1, vcc, 0, v3, vcc
	v_add_co_u32_e32 v2, vcc, s42, v4
	v_lshlrev_b32_e32 v30, 16, v30
	s_nop 0
	v_addc_co_u32_e32 v3, vcc, 0, v5, vcc
	v_add_co_u32_e32 v6, vcc, s43, v4
	v_lshlrev_b32_e32 v10, 16, v10
	s_nop 0
	v_addc_co_u32_e32 v7, vcc, 0, v5, vcc
	v_add_co_u32_e32 v8, vcc, s44, v4
	s_nop 1
	v_addc_co_u32_e32 v9, vcc, 0, v5, vcc
	flat_load_ushort v31, v[0:1]
	flat_load_ushort v32, v[0:1] offset:1024
	flat_load_ushort v33, v[2:3] offset:3072
	s_nop 0
	flat_load_ushort v2, v[0:1] offset:2048
	flat_load_ushort v34, v[6:7] offset:1024
	s_nop 0
	flat_load_ushort v8, v[8:9] offset:3072
	s_nop 0
	flat_load_ushort v0, v[0:1] offset:3072
	v_cvt_f32_f16_e32 v1, v12
	v_cvt_f32_f16_e32 v3, v13
	v_cvt_f32_f16_e32 v6, v15
	v_cvt_f32_f16_e32 v7, v18
	v_add_f32_e32 v9, 0, v1
	v_cvt_f32_f16_e32 v1, v19
	v_add_f32_e32 v12, v9, v3
	v_cvt_f32_f16_e32 v3, v20
	v_add_f32_e32 v13, v12, v6
	v_cvt_f32_f16_e32 v6, v22
	v_add_f32_e32 v15, v13, v7
	v_cvt_f32_f16_e32 v7, v25
	v_add_f32_e32 v18, v15, v1
	v_cvt_f32_f16_e32 v1, v26
	v_add_f32_e32 v19, v18, v3
	v_cvt_f32_f16_e32 v3, v27
	v_add_f32_e32 v20, v19, v6
	v_cvt_f32_f16_e32 v6, v29
	v_add_f32_e32 v22, v20, v7
	v_cvt_f32_f16_e32 v7, v11
	v_add_f32_e32 v11, v22, v1
	v_add_f32_e32 v25, v11, v3
	v_add_f32_e32 v26, v25, v6
	v_add_f32_e32 v27, v26, v7
	v_add_co_u32_e32 v6, vcc, s31, v4
	s_waitcnt vmcnt(0) lgkmcnt(0)
	v_cvt_f32_f16_e32 v1, v31
	v_cvt_f32_f16_e32 v3, v32
	v_addc_co_u32_e32 v7, vcc, 0, v5, vcc
	v_cvt_f32_f16_e32 v2, v2
	v_add_f32_e32 v29, v27, v1
	v_cvt_f32_f16_e32 v0, v0
	v_add_f32_e32 v31, v29, v3
	v_add_f32_e32 v32, v31, v2
	v_lshlrev_b32_e32 v33, 16, v33
	v_add_f32_e32 v35, v32, v0
	v_add_u32_e32 v0, s48, v81
	v_mad_i64_i32 v[0:1], s[60:61], v0, s3, v[74:75]
	v_lshl_add_u64 v[0:1], v[0:1], 0, s[16:17]
	ds_write_b32 v79, v35 offset:57344
	v_lshl_add_u64 v[0:1], v[0:1], 0, v[72:73]
	flat_load_dwordx4 v[0:3], v[0:1] offset:2048
	s_nop 0
	flat_load_ushort v36, v[4:5] offset:1024
	flat_load_ushort v37, v[6:7] offset:1024
	v_add_co_u32_e32 v6, vcc, s37, v4
	v_lshlrev_b32_e32 v34, 16, v34
	s_nop 0
	v_addc_co_u32_e32 v7, vcc, 0, v5, vcc
	v_add_co_u32_e32 v4, vcc, s41, v4
	flat_load_ushort v6, v[6:7] offset:1024
	s_nop 0
	v_addc_co_u32_e32 v5, vcc, 0, v5, vcc
	flat_load_ushort v7, v[4:5] offset:1024
	v_add_u32_e32 v4, s48, v82
	v_mad_i64_i32 v[4:5], s[22:23], v4, s3, v[74:75]
	v_lshl_add_u64 v[4:5], v[4:5], 0, s[16:17]
	v_lshl_add_u64 v[4:5], v[4:5], 0, v[72:73]
	flat_load_dwordx4 v[184:187], v[4:5] offset:2048
	v_add_u32_e32 v4, s48, v83
	v_mad_i64_i32 v[4:5], s[22:23], v4, s3, v[74:75]
	v_lshl_add_u64 v[4:5], v[4:5], 0, s[16:17]
	v_lshl_add_u64 v[4:5], v[4:5], 0, v[72:73]
	flat_load_dwordx4 v[188:191], v[4:5] offset:2048
	v_add_u32_e32 v4, s48, v84
	v_mad_i64_i32 v[4:5], s[22:23], v4, s3, v[74:75]
	v_lshl_add_u64 v[4:5], v[4:5], 0, s[16:17]
	v_lshl_add_u64 v[4:5], v[4:5], 0, v[72:73]
	flat_load_dwordx4 v[192:195], v[4:5] offset:2048
	v_lshlrev_b32_e32 v8, 16, v8
	s_waitcnt vmcnt(0) lgkmcnt(0)
	ds_write_b128 v93, v[0:3] offset:20480
	v_lshlrev_b32_e32 v6, 16, v6
	v_lshlrev_b32_e32 v7, 16, v7
	ds_write_b128 v94, v[184:187] offset:20480
	ds_write_b128 v93, v[188:191] offset:38912
	v_lshlrev_b32_e32 v4, 16, v36
	v_lshlrev_b32_e32 v5, 16, v14
	v_lshlrev_b32_e32 v14, 16, v16
	v_lshlrev_b32_e32 v16, 16, v17
	v_lshlrev_b32_e32 v17, 16, v37
	ds_write_b128 v95, v[192:195] offset:20480
	s_waitcnt lgkmcnt(0)
	s_barrier
	ds_read2st64_b32 v[0:1], v80 offset0:224 offset1:226
	ds_read2st64_b32 v[2:3], v80 offset0:228 offset1:230
	s_waitcnt lgkmcnt(1)
	v_add_f32_e32 v0, 0, v0
	v_cndmask_b32_e64 v36, v0, 0, s[6:7]
	v_add_f32_e32 v0, v0, v1
	v_add_f32_e32 v1, v1, v36
	v_cndmask_b32_e64 v1, v36, v1, s[8:9]
	s_waitcnt lgkmcnt(0)
	v_add_f32_e32 v0, v0, v2
	v_add_f32_e32 v2, v2, v1
	v_cndmask_b32_e64 v1, v1, v2, s[10:11]
	v_add_f32_e32 v2, v3, v1
	v_cndmask_b32_e64 v1, v1, v2, s[12:13]
	v_add_f32_e32 v0, v0, v3
	v_add_f32_e32 v2, v9, v1
	v_add_f32_e32 v3, v12, v1
	v_add_f32_e32 v9, v13, v1
	v_add_f32_e32 v12, v15, v1
	v_add_f32_e32 v13, v18, v1
	v_add_f32_e32 v15, v19, v1
	v_add_f32_e32 v18, v20, v1
	v_add_f32_e32 v19, v22, v1
	v_add_f32_e32 v11, v11, v1
	v_add_f32_e32 v20, v25, v1
	v_add_f32_e32 v22, v26, v1
	v_add_f32_e32 v25, v27, v1
	v_add_f32_e32 v26, v29, v1
	v_add_f32_e32 v27, v31, v1
	v_add_f32_e32 v29, v32, v1
	v_add_f32_e32 v1, v35, v1
	v_sub_f32_e32 v2, v0, v2
	v_sub_f32_e32 v3, v0, v3
	v_sub_f32_e32 v9, v0, v9
	v_sub_f32_e32 v12, v0, v12
	v_sub_f32_e32 v13, v0, v13
	v_sub_f32_e32 v15, v0, v15
	v_sub_f32_e32 v18, v0, v18
	v_sub_f32_e32 v19, v0, v19
	v_sub_f32_e32 v11, v0, v11
	v_sub_f32_e32 v20, v0, v20
	v_sub_f32_e32 v22, v0, v22
	v_sub_f32_e32 v25, v0, v25
	v_sub_f32_e32 v26, v0, v26
	v_sub_f32_e32 v27, v0, v27
	v_sub_f32_e32 v29, v0, v29
	v_sub_f32_e32 v1, v0, v1
	v_mul_f32_e32 v2, 0x3fb8aa3b, v2
	v_mul_f32_e32 v3, 0x3fb8aa3b, v3
	v_mul_f32_e32 v9, 0x3fb8aa3b, v9
	v_mul_f32_e32 v12, 0x3fb8aa3b, v12
	v_mul_f32_e32 v13, 0x3fb8aa3b, v13
	v_mul_f32_e32 v15, 0x3fb8aa3b, v15
	v_mul_f32_e32 v18, 0x3fb8aa3b, v18
	v_mul_f32_e32 v19, 0x3fb8aa3b, v19
	v_mul_f32_e32 v11, 0x3fb8aa3b, v11
	v_mul_f32_e32 v20, 0x3fb8aa3b, v20
	v_mul_f32_e32 v22, 0x3fb8aa3b, v22
	v_mul_f32_e32 v25, 0x3fb8aa3b, v25
	v_mul_f32_e32 v26, 0x3fb8aa3b, v26
	v_mul_f32_e32 v27, 0x3fb8aa3b, v27
	v_mul_f32_e32 v29, 0x3fb8aa3b, v29
	v_mul_f32_e32 v1, 0x3fb8aa3b, v1
	v_exp_f32_e32 v2, v2
	v_exp_f32_e32 v3, v3
	v_exp_f32_e32 v9, v9
	v_exp_f32_e32 v12, v12
	v_exp_f32_e32 v13, v13
	v_exp_f32_e32 v15, v15
	v_exp_f32_e32 v18, v18
	v_exp_f32_e32 v19, v19
	v_exp_f32_e32 v11, v11
	v_exp_f32_e32 v20, v20
	v_exp_f32_e32 v22, v22
	v_exp_f32_e32 v25, v25
	v_exp_f32_e32 v26, v26
	v_exp_f32_e32 v27, v27
	v_exp_f32_e32 v29, v29
	v_exp_f32_e32 v1, v1
	v_mul_f32_e32 v2, v2, v4
	v_mul_f32_e32 v3, v3, v5
	v_mul_f32_e32 v4, v9, v14
	v_mul_f32_e32 v5, v12, v16
	v_mul_f32_e32 v9, v13, v17
	v_mul_f32_e32 v12, v15, v21
	v_mul_f32_e32 v13, v18, v23
	v_mul_f32_e32 v14, v19, v24
	v_mul_f32_e32 v6, v11, v6
	v_mul_f32_e32 v11, v20, v28
	v_mul_f32_e32 v15, v22, v30
	v_mul_f32_e32 v10, v25, v10
	v_mul_f32_e32 v7, v26, v7
	v_mul_f32_e32 v16, v27, v33
	v_mul_f32_e32 v17, v29, v34
	v_mul_f32_e32 v1, v1, v8
	v_bfe_u32 v8, v2, 16, 1
	v_bfe_u32 v18, v3, 16, 1
	v_bfe_u32 v19, v4, 16, 1
	v_bfe_u32 v20, v5, 16, 1
	v_bfe_u32 v21, v9, 16, 1
	v_bfe_u32 v22, v12, 16, 1
	v_bfe_u32 v23, v13, 16, 1
	v_bfe_u32 v24, v14, 16, 1
	v_bfe_u32 v25, v6, 16, 1
	v_bfe_u32 v26, v11, 16, 1
	v_bfe_u32 v27, v15, 16, 1
	v_bfe_u32 v28, v10, 16, 1
	v_bfe_u32 v29, v7, 16, 1
	v_bfe_u32 v30, v16, 16, 1
	v_bfe_u32 v31, v17, 16, 1
	v_bfe_u32 v32, v1, 16, 1
	v_add3_u32 v2, v2, v8, s45
	v_add3_u32 v3, v3, v18, s45
	v_add3_u32 v4, v4, v19, s45
	v_add3_u32 v5, v5, v20, s45
	v_add3_u32 v8, v9, v21, s45
	v_add3_u32 v9, v12, v22, s45
	v_add3_u32 v12, v13, v23, s45
	v_add3_u32 v13, v14, v24, s45
	v_add3_u32 v6, v6, v25, s45
	v_add3_u32 v11, v11, v26, s45
	v_add3_u32 v14, v15, v27, s45
	v_add3_u32 v10, v10, v28, s45
	v_add3_u32 v7, v7, v29, s45
	v_add3_u32 v15, v16, v30, s45
	v_add3_u32 v16, v17, v31, s45
	v_add3_u32 v1, v1, v32, s45
	ds_write_b16_d16_hi v96, v2
	ds_write_b16_d16_hi v96, v3 offset:320
	ds_write_b16_d16_hi v96, v4 offset:640
	ds_write_b16_d16_hi v96, v5 offset:960
	ds_write_b16_d16_hi v96, v8 offset:1280
	ds_write_b16_d16_hi v96, v9 offset:1600
	ds_write_b16_d16_hi v96, v12 offset:1920
	ds_write_b16_d16_hi v96, v13 offset:2240
	ds_write_b16_d16_hi v96, v6 offset:2560
	ds_write_b16_d16_hi v96, v11 offset:2880
	ds_write_b16_d16_hi v96, v14 offset:3200
	ds_write_b16_d16_hi v96, v10 offset:3520
	ds_write_b16_d16_hi v96, v7 offset:3840
	ds_write_b16_d16_hi v96, v15 offset:4160
	ds_write_b16_d16_hi v96, v16 offset:4480
	ds_write_b16_d16_hi v96, v1 offset:4800
	s_and_saveexec_b64 s[22:23], s[6:7]
	s_cbranch_execz .LBB0_1121
	v_mul_f32_e32 v0, 0x3fb8aa3b, v0
	v_exp_f32_e32 v2, v0
	v_lshl_add_u64 v[0:1], s[50:51], 0, v[66:67]
	flat_store_dword v[0:1], v2
	s_branch .LBB0_1121

.LBB0_1509:
	v_add_u32_e32 v2, v65, v75
	s_waitcnt lgkmcnt(0)
	s_barrier
	ds_read_b64_tr_b16 v[0:1], v2 offset:34816
	ds_read_b64_tr_b16 v[2:3], v2 offset:37120
	ds_read_b128 v[4:7], v88
	v_add_u32_e32 v34, v65, v76
	s_waitcnt lgkmcnt(0)
	v_mfma_f32_32x32x16_bf16 v[16:31], v[4:7], v[0:3], 0
	ds_read_b128 v[4:7], v88 offset:4608
	ds_read_b64_tr_b16 v[32:33], v34 offset:34816
	ds_read_b64_tr_b16 v[34:35], v34 offset:37120
	ds_read_b128 v[56:59], v89
	s_lshl_b32 s66, s66, 1
	s_add_i32 s78, s78, s54
	s_add_i32 s57, s57, s59
	s_add_i32 s81, s81, s82
	v_lshl_add_u64 v[42:43], v[42:43], 0, s[72:73]
	s_waitcnt lgkmcnt(0)
	v_mfma_f32_32x32x16_bf16 v[16:31], v[56:59], v[32:35], v[16:31]
	ds_read_b128 v[56:59], v89 offset:4608
	v_lshl_add_u64 v[44:45], v[44:45], 0, s[72:73]
	v_lshl_add_u64 v[46:47], v[46:47], 0, s[72:73]
	v_lshl_add_u64 v[48:49], v[48:49], 0, s[72:73]
	v_lshl_add_u64 v[50:51], v[50:51], 0, s[72:73]
	s_cmpk_lt_i32 s78, 0x440
	v_mfma_f32_32x32x16_bf16 v[0:15], v[4:7], v[0:3], 0
	s_waitcnt lgkmcnt(0)
	v_mfma_f32_32x32x16_bf16 v[0:15], v[56:59], v[32:35], v[0:15]
	v_add_u32_e32 v34, v65, v77
	ds_read_b64_tr_b16 v[32:33], v34 offset:34816
	ds_read_b64_tr_b16 v[34:35], v34 offset:37120
	ds_read_b128 v[56:59], v90
	s_waitcnt lgkmcnt(0)
	v_mfma_f32_32x32x16_bf16 v[16:31], v[56:59], v[32:35], v[16:31]
	ds_read_b128 v[56:59], v90 offset:4608
	s_waitcnt lgkmcnt(0)
	v_mfma_f32_32x32x16_bf16 v[0:15], v[56:59], v[32:35], v[0:15]
	v_add_u32_e32 v34, v65, v78
	ds_read_b64_tr_b16 v[32:33], v34 offset:34816
	ds_read_b64_tr_b16 v[34:35], v34 offset:37120
	ds_read_b128 v[56:59], v91
	s_waitcnt lgkmcnt(0)
	v_mfma_f32_32x32x16_bf16 v[16:31], v[56:59], v[32:35], v[16:31]
	ds_read_b128 v[56:59], v91 offset:4608
	s_waitcnt lgkmcnt(0)
	v_mfma_f32_32x32x16_bf16 v[0:15], v[56:59], v[32:35], v[0:15]
	v_add_u32_e32 v34, v66, v75
	ds_read_b64_tr_b16 v[32:33], v34
	ds_read_b64_tr_b16 v[34:35], v34 offset:2304
	ds_read_b128 v[56:59], v92
	s_waitcnt lgkmcnt(0)
	v_mfma_f32_32x32x16_bf16 v[16:31], v[56:59], v[32:35], v[16:31]
	ds_read_b128 v[56:59], v92 offset:8704
	s_waitcnt lgkmcnt(0)
	v_mfma_f32_32x32x16_bf16 v[0:15], v[56:59], v[32:35], v[0:15]
	v_add_u32_e32 v34, v66, v76
	ds_read_b64_tr_b16 v[32:33], v34
	ds_read_b64_tr_b16 v[34:35], v34 offset:2304
	ds_read_b128 v[56:59], v93
	s_waitcnt lgkmcnt(0)
	v_mfma_f32_32x32x16_bf16 v[16:31], v[56:59], v[32:35], v[16:31]
	ds_read_b128 v[56:59], v93 offset:8704
	s_waitcnt lgkmcnt(0)
	v_mfma_f32_32x32x16_bf16 v[0:15], v[56:59], v[32:35], v[0:15]
	v_add_u32_e32 v34, v66, v77
	ds_read_b64_tr_b16 v[32:33], v34
	ds_read_b64_tr_b16 v[34:35], v34 offset:2304
	ds_read_b128 v[56:59], v94
	s_waitcnt lgkmcnt(0)
	v_mfma_f32_32x32x16_bf16 v[16:31], v[56:59], v[32:35], v[16:31]
	ds_read_b128 v[56:59], v94 offset:8704
	s_waitcnt lgkmcnt(0)
	v_mfma_f32_32x32x16_bf16 v[0:15], v[56:59], v[32:35], v[0:15]
	v_add_u32_e32 v34, v66, v78
	ds_read_b64_tr_b16 v[32:33], v34
	ds_read_b64_tr_b16 v[34:35], v34 offset:2304
	ds_read_b128 v[56:59], v95
	s_waitcnt lgkmcnt(0)
	v_mfma_f32_32x32x16_bf16 v[16:31], v[56:59], v[32:35], v[16:31]
	ds_read_b128 v[56:59], v95 offset:8704
	s_waitcnt lgkmcnt(0)
	v_mfma_f32_32x32x16_bf16 v[0:15], v[56:59], v[32:35], v[0:15]
	ds_read_b64_tr_b16 v[32:33], v96
	ds_read_b64_tr_b16 v[34:35], v96 offset:2304
	ds_read_b128 v[56:59], v97
	s_waitcnt lgkmcnt(0)
	v_mfma_f32_32x32x16_bf16 v[16:31], v[56:59], v[32:35], v[16:31]
	ds_read_b128 v[56:59], v97 offset:8704
	s_waitcnt lgkmcnt(0)
	v_mfma_f32_32x32x16_bf16 v[0:15], v[56:59], v[32:35], v[0:15]
	ds_read_b64_tr_b16 v[32:33], v98
	ds_read_b64_tr_b16 v[34:35], v98 offset:2304
	ds_read_b128 v[56:59], v99
	s_waitcnt lgkmcnt(0)
	v_mfma_f32_32x32x16_bf16 v[16:31], v[56:59], v[32:35], v[16:31]
	ds_read_b128 v[56:59], v99 offset:8704
	s_waitcnt lgkmcnt(0)
	v_mfma_f32_32x32x16_bf16 v[0:15], v[56:59], v[32:35], v[0:15]
	ds_read_b64_tr_b16 v[32:33], v100
	ds_read_b64_tr_b16 v[34:35], v100 offset:2304
	ds_read_b128 v[56:59], v101
	s_waitcnt lgkmcnt(0)
	v_mfma_f32_32x32x16_bf16 v[16:31], v[56:59], v[32:35], v[16:31]
	ds_read_b128 v[56:59], v101 offset:8704
	s_waitcnt lgkmcnt(0)
	v_mfma_f32_32x32x16_bf16 v[0:15], v[56:59], v[32:35], v[0:15]
	ds_read_b64_tr_b16 v[32:33], v102
	ds_read_b64_tr_b16 v[34:35], v102 offset:2304
	ds_read_b128 v[56:59], v103
	s_waitcnt lgkmcnt(0)
	v_mfma_f32_32x32x16_bf16 v[16:31], v[56:59], v[32:35], v[16:31]
	ds_read_b128 v[56:59], v103 offset:8704
	s_waitcnt lgkmcnt(0)
	s_barrier
	v_mfma_f32_32x32x16_bf16 v[0:15], v[56:59], v[32:35], v[0:15]
	s_nop 7
	ds_write_b32 v104, v16
	ds_write_b32 v104, v17 offset:1040
	ds_write_b32 v104, v18 offset:2080
	ds_write_b32 v104, v19 offset:3120
	ds_write_b32 v104, v20 offset:8320
	ds_write_b32 v104, v21 offset:9360
	ds_write_b32 v104, v22 offset:10400
	ds_write_b32 v104, v23 offset:11440
	ds_write_b32 v104, v24 offset:16640
	ds_write_b32 v104, v25 offset:17680
	ds_write_b32 v104, v26 offset:18720
	ds_write_b32 v104, v27 offset:19760
	ds_write_b32 v104, v28 offset:24960
	ds_write_b32 v104, v29 offset:26000
	ds_write_b32 v104, v30 offset:27040
	ds_write_b32 v104, v31 offset:28080
	ds_write_b32 v104, v0 offset:33280
	ds_write_b32 v104, v1 offset:34320
	ds_write_b32 v104, v2 offset:35360
	ds_write_b32 v104, v3 offset:36400
	ds_write_b32 v104, v4 offset:41600
	ds_write_b32 v104, v5 offset:42640
	ds_write_b32 v104, v6 offset:43680
	ds_write_b32 v104, v7 offset:44720
	ds_write_b32 v104, v8 offset:49920
	ds_write_b32 v104, v9 offset:50960
	ds_write_b32 v104, v10 offset:52000
	ds_write_b32 v104, v11 offset:53040
	ds_write_b32 v104, v12 offset:58240
	ds_write_b32 v104, v13 offset:59280
	ds_write_b32 v104, v14 offset:60320
	ds_write_b32 v104, v15 offset:61360
	s_waitcnt lgkmcnt(0)
	s_barrier
	ds_read_b128 v[28:31], v105
	ds_read_b128 v[24:27], v105 offset:128
	ds_read_b128 v[20:23], v105 offset:256
	ds_read_b128 v[16:19], v105 offset:384
	ds_read_b128 v[12:15], v105 offset:512
	ds_read_b128 v[8:11], v105 offset:640
	s_waitcnt lgkmcnt(5)
	v_mov_b32_e32 v2, v29
	s_waitcnt lgkmcnt(4)
	v_mov_b32_e32 v3, v25
	v_mov_b32_e32 v0, v28
	v_mov_b32_e32 v1, v24
	v_pk_mul_f32 v[2:3], v[2:3], v[2:3]
	v_mov_b32_e32 v4, v31
	v_mov_b32_e32 v5, v27
	v_pk_fma_f32 v[0:1], v[0:1], v[0:1], v[2:3]
	v_mov_b32_e32 v2, v30
	v_mov_b32_e32 v3, v26
	v_pk_mul_f32 v[4:5], v[4:5], v[4:5]
	s_nop 0
	v_pk_fma_f32 v[2:3], v[2:3], v[2:3], v[4:5]
	s_waitcnt lgkmcnt(3)
	v_pk_mul_f32 v[4:5], v[20:21], v[20:21]
	v_pk_add_f32 v[0:1], v[0:1], v[2:3]
	v_pk_mul_f32 v[2:3], v[22:23], v[22:23]
	v_pk_add_f32 v[0:1], v[0:1], v[0:1] op_sel:[0,1] op_sel_hi:[1,0]
	v_pk_mov_b32 v[6:7], v[4:5], v[2:3] op_sel:[1,0]
	v_mov_b32_e32 v5, v3
	v_pk_add_f32 v[2:3], v[6:7], v[4:5]
	s_waitcnt lgkmcnt(1)
	v_mul_f32_e32 v4, v12, v12
	v_mul_f32_e32 v5, v13, v13
	v_pk_add_f32 v[2:3], v[2:3], v[2:3] op_sel:[0,1] op_sel_hi:[1,0]
	v_mov_b32_e32 v1, v4
	v_mov_b32_e32 v3, v5
	v_pk_add_f32 v[0:1], v[0:1], v[2:3]
	v_mul_f32_e32 v2, v17, v17
	v_mul_f32_e32 v4, v19, v19
	v_mul_f32_e32 v6, v14, v14
	v_mul_f32_e32 v7, v15, v15
	v_pk_fma_f32 v[2:3], v[16:17], v[16:17], v[2:3] op_sel_hi:[1,1,0]
	v_pk_fma_f32 v[4:5], v[18:19], v[18:19], v[4:5] op_sel_hi:[1,1,0]
	v_mov_b32_e32 v3, v6
	v_mov_b32_e32 v5, v7
	v_pk_add_f32 v[2:3], v[2:3], v[4:5]
	s_nop 0
	v_pk_add_f32 v[32:33], v[0:1], v[2:3]
	s_waitcnt lgkmcnt(0)
	v_pk_mul_f32 v[0:1], v[10:11], v[10:11]
	v_pk_mul_f32 v[2:3], v[8:9], v[8:9]
	v_pk_add_f32 v[32:33], v[32:33], v[32:33] op_sel:[0,1] op_sel_hi:[1,0]
	v_pk_mov_b32 v[4:5], v[2:3], v[0:1] op_sel:[1,0]
	v_mov_b32_e32 v3, v1
	v_pk_add_f32 v[34:35], v[4:5], v[2:3]
	ds_read_b128 v[4:7], v105 offset:768
	ds_read_b128 v[0:3], v105 offset:896
	v_pk_add_f32 v[34:35], v[34:35], v[34:35] op_sel:[0,1] op_sel_hi:[1,0]
	s_waitcnt lgkmcnt(0)
	v_mul_f32_e32 v53, v0, v0
	v_mul_f32_e32 v55, v1, v1
	v_mov_b32_e32 v33, v53
	v_mov_b32_e32 v35, v55
	v_pk_add_f32 v[32:33], v[32:33], v[34:35]
	v_mul_f32_e32 v34, v5, v5
	v_mul_f32_e32 v56, v2, v2
	v_pk_fma_f32 v[34:35], v[4:5], v[4:5], v[34:35] op_sel_hi:[1,1,0]
	v_mul_f32_e32 v58, v3, v3
	v_mov_b32_e32 v35, v56
	v_mul_f32_e32 v56, v7, v7
	v_pk_fma_f32 v[56:57], v[6:7], v[6:7], v[56:57] op_sel_hi:[1,1,0]
	s_nop 0
	v_mov_b32_e32 v57, v58
	v_pk_add_f32 v[34:35], v[34:35], v[56:57]
	s_nop 0
	v_pk_add_f32 v[32:33], v[32:33], v[34:35]
	v_and_b32_e32 v35, 64, v108
	v_xor_b32_e32 v34, 1, v108
	v_add_u32_e32 v35, 64, v35
	v_cmp_lt_i32_e32 vcc, v34, v35
	v_add_f32_e32 v33, v32, v33
	v_add_u32_e32 v32, s33, v67
	v_cndmask_b32_e32 v34, v108, v34, vcc
	v_lshlrev_b32_e32 v34, 2, v34
	ds_bpermute_b32 v34, v34, v33
	s_waitcnt lgkmcnt(0)
	v_add_f32_e32 v33, v33, v34
	v_xor_b32_e32 v34, 2, v108
	v_cmp_lt_i32_e32 vcc, v34, v35
	s_nop 1
	v_cndmask_b32_e32 v34, v108, v34, vcc
	v_lshlrev_b32_e32 v34, 2, v34
	ds_bpermute_b32 v34, v34, v33
	s_waitcnt lgkmcnt(0)
	v_add_f32_e32 v33, v33, v34
	v_xor_b32_e32 v34, 4, v108
	v_cmp_lt_i32_e32 vcc, v34, v35
	s_nop 1
	v_cndmask_b32_e32 v34, v108, v34, vcc
	v_lshlrev_b32_e32 v34, 2, v34
	ds_bpermute_b32 v34, v34, v33
	s_waitcnt lgkmcnt(0)
	v_add_f32_e32 v33, v33, v34
	v_fmamk_f32 v33, v33, 0x3b800000, v106
	v_cmp_gt_f32_e32 vcc, s97, v33
	v_mul_f32_e32 v34, 0x4f800000, v33
	s_nop 0
	v_cndmask_b32_e32 v33, v33, v34, vcc
	v_sqrt_f32_e32 v34, v33
	s_nop 0
	v_add_u32_e32 v35, -1, v34
	v_fma_f32 v53, -v35, v34, v33
	v_cmp_ge_f32_e64 s[48:49], 0, v53
	v_add_u32_e32 v53, 1, v34
	s_nop 0
	v_cndmask_b32_e64 v35, v34, v35, s[48:49]
	v_fma_f32 v34, -v53, v34, v33
	v_cmp_lt_f32_e64 s[48:49], 0, v34
	s_nop 1
	v_cndmask_b32_e64 v34, v35, v53, s[48:49]
	v_mul_f32_e32 v35, 0x37800000, v34
	v_cndmask_b32_e32 v34, v34, v35, vcc
	v_cmp_class_f32_e32 vcc, v33, v107
	s_nop 1
	v_cndmask_b32_e32 v33, v34, v33, vcc
	v_div_scale_f32 v34, s[48:49], v33, v33, 1.0
	v_rcp_f32_e32 v35, v34
	s_nop 0
	v_fma_f32 v53, -v34, v35, 1.0
	v_fmac_f32_e32 v35, v53, v35
	v_div_scale_f32 v53, vcc, 1.0, v33, 1.0
	v_mul_f32_e32 v55, v53, v35
	v_fma_f32 v56, -v34, v55, v53
	v_fmac_f32_e32 v55, v56, v35
	v_fma_f32 v34, -v34, v55, v53
	v_div_fmas_f32 v34, v34, v35, v55
	v_div_fixup_f32 v53, v34, v33, 1.0
	v_ashrrev_i32_e32 v33, 31, v32
	v_mov_b64_e32 v[34:35], s[60:61]
	v_mad_i64_i32 v[34:35], s[48:49], v32, s3, v[34:35]
	v_lshlrev_b64 v[32:33], 11, v[32:33]
	v_lshl_add_u64 v[34:35], v[34:35], 0, s[66:67]
	v_lshl_add_u64 v[32:33], s[64:65], 0, v[32:33]
	v_mov_b32_e32 v55, v37
	v_lshl_add_u64 v[58:59], v[32:33], 0, s[66:67]
	v_lshl_add_u64 v[32:33], v[34:35], 0, v[54:55]
	v_lshl_add_u64 v[56:57], v[32:33], 0, s[74:75]
	v_add_co_u32_e32 v32, vcc, s83, v32
	v_mul_f32_e32 v113, v28, v53
	s_nop 0
	v_addc_co_u32_e32 v33, vcc, 0, v33, vcc
	global_load_dwordx2 v[110:111], v[32:33], off
	s_nop 0
	global_load_dwordx4 v[32:35], v[40:41], off
	global_load_dwordx2 v[184:185], v[56:57], off offset:64
	global_load_dwordx4 v[188:191], v[40:41], off offset:128
	global_load_dwordx2 v[192:193], v[56:57], off offset:128
	global_load_dwordx4 v[196:199], v[40:41], off offset:256
	global_load_dwordx2 v[200:201], v[56:57], off offset:192
	global_load_dwordx4 v[204:207], v[40:41], off offset:384
	global_load_dwordx2 v[208:209], v[56:57], off offset:256
	global_load_dwordx4 v[212:215], v[40:41], off offset:512
	global_load_dwordx2 v[216:217], v[56:57], off offset:320
	global_load_dwordx4 v[220:223], v[40:41], off offset:640
	global_load_dwordx2 v[224:225], v[56:57], off offset:384
	global_load_dwordx4 v[228:231], v[40:41], off offset:768
	global_load_dwordx2 v[232:233], v[56:57], off offset:448
	global_load_dwordx4 v[236:239], v[40:41], off offset:896
	v_mul_f32_e32 v115, v30, v53
	v_mul_f32_e32 v117, v31, v53
	s_waitcnt vmcnt(14) lgkmcnt(0)
	v_lshlrev_b32_e32 v112, 16, v110
	v_mul_f32_e32 v28, 0xbfb8aa3b, v112
	v_exp_f32_e32 v28, v28
	v_and_b32_e32 v110, 0xffff0000, v110
	v_mov_b32_e32 v119, v32
	v_lshlrev_b32_e32 v114, 16, v111
	v_add_f32_e32 v28, 1.0, v28
	v_rcp_f32_e32 v118, v28
	v_mul_f32_e32 v28, 0xbfb8aa3b, v110
	v_exp_f32_e32 v28, v28
	v_and_b32_e32 v116, 0xffff0000, v111
	v_mul_f32_e32 v111, v29, v53
	v_pk_mul_f32 v[112:113], v[118:119], v[112:113]
	v_add_f32_e32 v28, 1.0, v28
	v_rcp_f32_e32 v32, v28
	v_mul_f32_e32 v109, v112, v113
	v_mul_f32_e32 v112, v26, v53
	v_pk_mul_f32 v[28:29], v[32:33], v[110:111]
	s_nop 0
	v_mul_f32_e32 v28, v28, v29
	v_cvt_pk_bf16_f32 v32, v109, v28
	v_mul_f32_e32 v28, 0xbfb8aa3b, v114
	v_exp_f32_e32 v28, v28
	v_mov_b32_e32 v29, v34
	v_mul_f32_e32 v110, v25, v53
	v_add_f32_e32 v28, 1.0, v28
	v_rcp_f32_e32 v28, v28
	s_nop 0
	v_pk_mul_f32 v[28:29], v[28:29], v[114:115]
	s_nop 0
	v_mul_f32_e32 v30, v28, v29
	v_mul_f32_e32 v28, 0xbfb8aa3b, v116
	v_exp_f32_e32 v28, v28
	s_nop 0
	v_add_f32_e32 v28, 1.0, v28
	v_rcp_f32_e32 v34, v28
	s_nop 0
	v_pk_mul_f32 v[28:29], v[34:35], v[116:117]
	s_nop 0
	v_mul_f32_e32 v28, v28, v29
	v_cvt_pk_bf16_f32 v33, v30, v28
	v_lshl_add_u64 v[28:29], v[58:59], 0, v[54:55]
	global_store_dwordx2 v[28:29], v[32:33], off
	s_nop 0
	v_mul_f32_e32 v58, v24, v53
	s_waitcnt vmcnt(13) lgkmcnt(0)
	v_mov_b64_e32 v[34:35], v[184:185]
	v_mov_b64_e32 v[30:31], v[188:189]
	v_mov_b64_e32 v[32:33], v[190:191]
	v_lshlrev_b32_e32 v59, 16, v34
	v_mul_f32_e32 v24, 0xbfb8aa3b, v59
	v_exp_f32_e32 v24, v24
	v_and_b32_e32 v111, 0xffff0000, v34
	v_lshlrev_b32_e32 v113, 16, v35
	v_and_b32_e32 v35, 0xffff0000, v35
	v_add_f32_e32 v24, 1.0, v24
	v_rcp_f32_e32 v115, v24
	v_mul_f32_e32 v24, 0xbfb8aa3b, v111
	v_exp_f32_e32 v24, v24
	v_mul_f32_e32 v26, 0xbfb8aa3b, v35
	v_exp_f32_e32 v26, v26
	v_mov_b32_e32 v114, v30
	v_add_f32_e32 v24, 1.0, v24
	v_rcp_f32_e32 v25, v24
	v_mov_b32_e32 v24, v31
	v_add_f32_e32 v26, 1.0, v26
	v_pk_mul_f32 v[58:59], v[114:115], v[58:59]
	v_pk_mul_f32 v[24:25], v[24:25], v[110:111]
	v_mul_f32_e32 v34, v27, v53
	v_mul_f32_e32 v24, v24, v25
	v_mul_f32_e32 v25, 0xbfb8aa3b, v113
	v_exp_f32_e32 v25, v25
	v_rcp_f32_e32 v27, v26
	v_mul_f32_e32 v30, v58, v59
	v_cvt_pk_bf16_f32 v24, v30, v24
	v_add_f32_e32 v25, 1.0, v25
	v_rcp_f32_e32 v31, v25
	v_mov_b32_e32 v30, v32
	v_mov_b32_e32 v26, v33
	v_pk_mul_f32 v[26:27], v[26:27], v[34:35]
	v_pk_mul_f32 v[30:31], v[30:31], v[112:113]
	v_mul_f32_e32 v26, v26, v27
	v_mul_f32_e32 v25, v30, v31
	v_cvt_pk_bf16_f32 v25, v25, v26
	global_store_dwordx2 v[28:29], v[24:25], off offset:64
	s_nop 0
	v_mul_f32_e32 v110, v20, v53
	s_waitcnt vmcnt(12) lgkmcnt(0)
	v_mov_b64_e32 v[30:31], v[192:193]
	v_mov_b64_e32 v[24:25], v[196:197]
	v_mov_b64_e32 v[26:27], v[198:199]
	v_lshlrev_b32_e32 v33, 16, v30
	v_mul_f32_e32 v20, 0xbfb8aa3b, v33
	v_exp_f32_e32 v20, v20
	v_and_b32_e32 v35, 0xffff0000, v30
	v_mov_b32_e32 v32, v24
	v_mov_b32_e32 v34, v25
	v_add_f32_e32 v20, 1.0, v20
	v_rcp_f32_e32 v111, v20
	v_mul_f32_e32 v20, v21, v53
	v_mul_f32_e32 v21, 0xbfb8aa3b, v35
	v_exp_f32_e32 v21, v21
	v_lshlrev_b32_e32 v59, 16, v31
	v_pk_mul_f32 v[32:33], v[110:111], v[32:33]
	v_and_b32_e32 v31, 0xffff0000, v31
	v_add_f32_e32 v21, 1.0, v21
	v_rcp_f32_e32 v21, v21
	v_mul_f32_e32 v24, v32, v33
	v_mov_b32_e32 v58, v26
	v_mov_b32_e32 v30, v27
	v_pk_mul_f32 v[20:21], v[20:21], v[34:35]
	v_mul_f32_e32 v34, v16, v53
	v_mul_f32_e32 v20, v20, v21
	v_mul_f32_e32 v21, 0xbfb8aa3b, v59
	v_cvt_pk_bf16_f32 v20, v24, v20
	v_mul_f32_e32 v24, v22, v53
	v_exp_f32_e32 v21, v21
	v_mul_f32_e32 v22, v23, v53
	v_mul_f32_e32 v23, 0xbfb8aa3b, v31
	v_exp_f32_e32 v23, v23
	v_add_f32_e32 v21, 1.0, v21
	v_rcp_f32_e32 v25, v21
	v_add_f32_e32 v23, 1.0, v23
	v_rcp_f32_e32 v23, v23
	v_pk_mul_f32 v[24:25], v[24:25], v[58:59]
	v_pk_mul_f32 v[22:23], v[22:23], v[30:31]
	v_mul_f32_e32 v21, v24, v25
	v_mul_f32_e32 v22, v22, v23
	v_cvt_pk_bf16_f32 v21, v21, v22
	global_store_dwordx2 v[28:29], v[20:21], off offset:128
	s_nop 0
	s_waitcnt vmcnt(11) lgkmcnt(0)
	v_mov_b64_e32 v[24:25], v[200:201]
	v_mov_b64_e32 v[20:21], v[204:205]
	v_mov_b64_e32 v[22:23], v[206:207]
	v_lshlrev_b32_e32 v27, 16, v24
	v_mul_f32_e32 v16, 0xbfb8aa3b, v27
	v_exp_f32_e32 v16, v16
	v_and_b32_e32 v31, 0xffff0000, v24
	v_mov_b32_e32 v26, v20
	v_mov_b32_e32 v30, v21
	v_add_f32_e32 v16, 1.0, v16
	v_rcp_f32_e32 v35, v16
	v_mul_f32_e32 v16, v17, v53
	v_mul_f32_e32 v17, 0xbfb8aa3b, v31
	v_exp_f32_e32 v17, v17
	v_lshlrev_b32_e32 v33, 16, v25
	v_pk_mul_f32 v[26:27], v[34:35], v[26:27]
	v_and_b32_e32 v25, 0xffff0000, v25
	v_add_f32_e32 v17, 1.0, v17
	v_rcp_f32_e32 v17, v17
	v_mul_f32_e32 v20, v26, v27
	v_mov_b32_e32 v32, v22
	v_mov_b32_e32 v24, v23
	v_pk_mul_f32 v[16:17], v[16:17], v[30:31]
	v_mul_f32_e32 v30, v12, v53
	v_mul_f32_e32 v16, v16, v17
	v_mul_f32_e32 v17, 0xbfb8aa3b, v33
	v_cvt_pk_bf16_f32 v16, v20, v16
	v_mul_f32_e32 v20, v18, v53
	v_exp_f32_e32 v17, v17
	v_mul_f32_e32 v18, v19, v53
	v_mul_f32_e32 v19, 0xbfb8aa3b, v25
	v_exp_f32_e32 v19, v19
	v_add_f32_e32 v17, 1.0, v17
	v_rcp_f32_e32 v21, v17
	v_add_f32_e32 v19, 1.0, v19
	v_rcp_f32_e32 v19, v19
	v_pk_mul_f32 v[20:21], v[20:21], v[32:33]
	v_pk_mul_f32 v[18:19], v[18:19], v[24:25]
	v_mul_f32_e32 v17, v20, v21
	v_mul_f32_e32 v18, v18, v19
	v_cvt_pk_bf16_f32 v17, v17, v18
	global_store_dwordx2 v[28:29], v[16:17], off offset:192
	s_nop 0
	s_waitcnt vmcnt(10) lgkmcnt(0)
	v_mov_b64_e32 v[20:21], v[208:209]
	v_mov_b64_e32 v[16:17], v[212:213]
	v_mov_b64_e32 v[18:19], v[214:215]
	v_lshlrev_b32_e32 v23, 16, v20
	v_mul_f32_e32 v12, 0xbfb8aa3b, v23
	v_exp_f32_e32 v12, v12
	v_and_b32_e32 v25, 0xffff0000, v20
	v_mov_b32_e32 v22, v16
	v_mov_b32_e32 v24, v17
	v_add_f32_e32 v12, 1.0, v12
	v_rcp_f32_e32 v31, v12
	v_mul_f32_e32 v12, v13, v53
	v_mul_f32_e32 v13, 0xbfb8aa3b, v25
	v_exp_f32_e32 v13, v13
	v_lshlrev_b32_e32 v27, 16, v21
	v_pk_mul_f32 v[22:23], v[30:31], v[22:23]
	v_and_b32_e32 v21, 0xffff0000, v21
	v_add_f32_e32 v13, 1.0, v13
	v_rcp_f32_e32 v13, v13
	v_mul_f32_e32 v16, v22, v23
	v_mov_b32_e32 v26, v18
	v_mov_b32_e32 v20, v19
	v_pk_mul_f32 v[12:13], v[12:13], v[24:25]
	v_mul_f32_e32 v24, v8, v53
	v_mul_f32_e32 v12, v12, v13
	v_mul_f32_e32 v13, 0xbfb8aa3b, v27
	v_cvt_pk_bf16_f32 v12, v16, v12
	v_mul_f32_e32 v16, v14, v53
	v_exp_f32_e32 v13, v13
	v_mul_f32_e32 v14, v15, v53
	v_mul_f32_e32 v15, 0xbfb8aa3b, v21
	v_exp_f32_e32 v15, v15
	v_add_f32_e32 v13, 1.0, v13
	v_rcp_f32_e32 v17, v13
	v_add_f32_e32 v15, 1.0, v15
	v_rcp_f32_e32 v15, v15
	v_pk_mul_f32 v[16:17], v[16:17], v[26:27]
	v_pk_mul_f32 v[14:15], v[14:15], v[20:21]
	v_mul_f32_e32 v13, v16, v17
	v_mul_f32_e32 v14, v14, v15
	v_cvt_pk_bf16_f32 v13, v13, v14
	global_store_dwordx2 v[28:29], v[12:13], off offset:256
	s_nop 0
	s_waitcnt vmcnt(9) lgkmcnt(0)
	v_mov_b64_e32 v[16:17], v[216:217]
	v_mov_b64_e32 v[12:13], v[220:221]
	v_mov_b64_e32 v[14:15], v[222:223]
	v_lshlrev_b32_e32 v19, 16, v16
	v_mul_f32_e32 v8, 0xbfb8aa3b, v19
	v_exp_f32_e32 v8, v8
	v_and_b32_e32 v21, 0xffff0000, v16
	v_mov_b32_e32 v18, v12
	v_mov_b32_e32 v20, v13
	v_add_f32_e32 v8, 1.0, v8
	v_rcp_f32_e32 v25, v8
	v_mul_f32_e32 v8, v9, v53
	v_mul_f32_e32 v9, 0xbfb8aa3b, v21
	v_exp_f32_e32 v9, v9
	v_lshlrev_b32_e32 v23, 16, v17
	v_pk_mul_f32 v[18:19], v[24:25], v[18:19]
	v_and_b32_e32 v17, 0xffff0000, v17
	v_add_f32_e32 v9, 1.0, v9
	v_rcp_f32_e32 v9, v9
	v_mul_f32_e32 v12, v18, v19
	v_mov_b32_e32 v22, v14
	v_mov_b32_e32 v16, v15
	v_pk_mul_f32 v[8:9], v[8:9], v[20:21]
	v_mul_f32_e32 v20, v4, v53
	v_mul_f32_e32 v8, v8, v9
	v_mul_f32_e32 v9, 0xbfb8aa3b, v23
	v_cvt_pk_bf16_f32 v8, v12, v8
	v_mul_f32_e32 v12, v10, v53
	v_exp_f32_e32 v9, v9
	v_mul_f32_e32 v10, v11, v53
	v_mul_f32_e32 v11, 0xbfb8aa3b, v17
	v_exp_f32_e32 v11, v11
	v_add_f32_e32 v9, 1.0, v9
	v_rcp_f32_e32 v13, v9
	v_add_f32_e32 v11, 1.0, v11
	v_rcp_f32_e32 v11, v11
	v_pk_mul_f32 v[12:13], v[12:13], v[22:23]
	v_pk_mul_f32 v[10:11], v[10:11], v[16:17]
	v_mul_f32_e32 v9, v12, v13
	v_mul_f32_e32 v10, v10, v11
	v_cvt_pk_bf16_f32 v9, v9, v10
	global_store_dwordx2 v[28:29], v[8:9], off offset:320
	s_nop 0
	s_waitcnt vmcnt(8) lgkmcnt(0)
	v_mov_b64_e32 v[12:13], v[224:225]
	v_mov_b64_e32 v[8:9], v[228:229]
	v_mov_b64_e32 v[10:11], v[230:231]
	v_lshlrev_b32_e32 v15, 16, v12
	v_mul_f32_e32 v4, 0xbfb8aa3b, v15
	v_exp_f32_e32 v4, v4
	v_and_b32_e32 v17, 0xffff0000, v12
	v_mov_b32_e32 v14, v8
	v_mov_b32_e32 v16, v9
	v_add_f32_e32 v4, 1.0, v4
	v_rcp_f32_e32 v21, v4
	v_mul_f32_e32 v4, v5, v53
	v_mul_f32_e32 v5, 0xbfb8aa3b, v17
	v_exp_f32_e32 v5, v5
	v_lshlrev_b32_e32 v19, 16, v13
	v_pk_mul_f32 v[14:15], v[20:21], v[14:15]
	v_and_b32_e32 v13, 0xffff0000, v13
	v_add_f32_e32 v5, 1.0, v5
	v_rcp_f32_e32 v5, v5
	v_mul_f32_e32 v8, v14, v15
	v_mov_b32_e32 v18, v10
	v_mov_b32_e32 v12, v11
	v_pk_mul_f32 v[4:5], v[4:5], v[16:17]
	v_mul_f32_e32 v16, v0, v53
	v_mul_f32_e32 v4, v4, v5
	v_mul_f32_e32 v5, 0xbfb8aa3b, v19
	v_cvt_pk_bf16_f32 v4, v8, v4
	v_mul_f32_e32 v8, v6, v53
	v_exp_f32_e32 v5, v5
	v_mul_f32_e32 v6, v7, v53
	v_mul_f32_e32 v7, 0xbfb8aa3b, v13
	v_exp_f32_e32 v7, v7
	v_add_f32_e32 v5, 1.0, v5
	v_rcp_f32_e32 v9, v5
	v_add_f32_e32 v7, 1.0, v7
	v_rcp_f32_e32 v7, v7
	v_pk_mul_f32 v[8:9], v[8:9], v[18:19]
	v_pk_mul_f32 v[6:7], v[6:7], v[12:13]
	v_mul_f32_e32 v5, v8, v9
	v_mul_f32_e32 v6, v6, v7
	v_cvt_pk_bf16_f32 v5, v5, v6
	global_store_dwordx2 v[28:29], v[4:5], off offset:384
	s_nop 0
	s_waitcnt vmcnt(7) lgkmcnt(0)
	v_mov_b64_e32 v[8:9], v[232:233]
	v_mov_b64_e32 v[4:5], v[236:237]
	v_mov_b64_e32 v[6:7], v[238:239]
	v_lshlrev_b32_e32 v11, 16, v8
	v_mul_f32_e32 v0, 0xbfb8aa3b, v11
	v_exp_f32_e32 v0, v0
	v_and_b32_e32 v13, 0xffff0000, v8
	v_mov_b32_e32 v10, v4
	v_mov_b32_e32 v12, v5
	v_add_f32_e32 v0, 1.0, v0
	v_rcp_f32_e32 v17, v0
	v_mul_f32_e32 v0, v1, v53
	v_mul_f32_e32 v1, 0xbfb8aa3b, v13
	v_exp_f32_e32 v1, v1
	v_lshlrev_b32_e32 v15, 16, v9
	v_pk_mul_f32 v[10:11], v[16:17], v[10:11]
	v_and_b32_e32 v9, 0xffff0000, v9
	v_add_f32_e32 v1, 1.0, v1
	v_rcp_f32_e32 v1, v1
	v_mul_f32_e32 v4, v10, v11
	v_mov_b32_e32 v14, v6
	v_mov_b32_e32 v8, v7
	v_pk_mul_f32 v[0:1], v[0:1], v[12:13]
	s_nop 0
	v_mul_f32_e32 v0, v0, v1
	v_mul_f32_e32 v1, 0xbfb8aa3b, v15
	v_cvt_pk_bf16_f32 v0, v4, v0
	v_mul_f32_e32 v4, v2, v53
	v_exp_f32_e32 v1, v1
	v_mul_f32_e32 v2, v3, v53
	v_mul_f32_e32 v3, 0xbfb8aa3b, v9
	v_exp_f32_e32 v3, v3
	v_add_f32_e32 v1, 1.0, v1
	v_rcp_f32_e32 v5, v1
	v_add_f32_e32 v3, 1.0, v3
	v_rcp_f32_e32 v3, v3
	v_pk_mul_f32 v[4:5], v[4:5], v[14:15]
	v_pk_mul_f32 v[2:3], v[2:3], v[8:9]
	v_mul_f32_e32 v1, v4, v5
	v_mul_f32_e32 v2, v2, v3
	v_cvt_pk_bf16_f32 v1, v1, v2
	global_store_dwordx2 v[28:29], v[0:1], off offset:448
	s_waitcnt lgkmcnt(0)
	s_barrier
	s_cbranch_scc0 .LBB0_1525

.LBB0_1514:
	v_add_u32_e32 v2, s33, v60
	s_and_b32 s48, s48, 1
	v_ashrrev_i32_e32 v3, 31, v2
	s_or_b32 s48, s48, 2
	v_lshlrev_b64 v[0:1], 10, v[2:3]
	v_lshl_add_u64 v[0:1], s[62:63], 0, v[0:1]
	s_lshl_b32 s66, s48, 8
	v_lshl_add_u64 v[0:1], v[0:1], 0, s[66:67]
	v_lshl_add_u64 v[4:5], v[0:1], 0, v[36:37]
	flat_load_ushort v6, v[4:5]
	v_mov_b64_e32 v[0:1], s[60:61]
	v_mad_i64_i32 v[2:3], vcc, v2, s3, v[0:1]
	v_lshl_add_u64 v[2:3], v[2:3], 0, s[66:67]
	v_lshl_add_u64 v[2:3], v[2:3], 0, v[36:37]
	v_add_co_u32_e32 v12, vcc, s83, v2
	s_movk_i32 s49, 0x4000
	s_nop 0
	v_addc_co_u32_e32 v13, vcc, 0, v3, vcc
	v_add_u32_e32 v53, s33, v68
	s_lshl_b32 s48, s48, 9
	v_add_u32_e32 v124, v62, v71
	s_waitcnt vmcnt(0) lgkmcnt(0)
	v_cvt_f32_f16_e32 v7, v6
	v_mov_b32_e32 v6, 0
	v_add_f32_e32 v8, 0, v7
	flat_load_ushort v10, v[2:3]
	flat_load_ushort v11, v[2:3] offset:1024
	flat_load_ushort v7, v[4:5] offset:1024
	flat_load_ushort v14, v[12:13] offset:2048
	flat_load_ushort v15, v[12:13] offset:3072
	flat_load_ushort v9, v[4:5] offset:2048
	v_add_co_u32_e32 v12, vcc, s84, v2
	s_waitcnt vmcnt(0) lgkmcnt(0)
	v_cvt_f32_f16_e32 v7, v7
	v_addc_co_u32_e32 v13, vcc, 0, v3, vcc
	v_add_co_u32_e32 v16, vcc, s49, v2
	s_movk_i32 s49, 0x6000
	s_nop 0
	v_addc_co_u32_e32 v17, vcc, 0, v3, vcc
	v_add_co_u32_e32 v20, vcc, s83, v4
	flat_load_ushort v18, v[12:13]
	flat_load_ushort v19, v[12:13] offset:1024
	s_nop 0
	flat_load_ushort v12, v[4:5] offset:3072
	v_addc_co_u32_e32 v21, vcc, 0, v5, vcc
	flat_load_ushort v23, v[16:17] offset:2048
	flat_load_ushort v24, v[16:17] offset:3072
	v_add_co_u32_e32 v16, vcc, s49, v2
	s_movk_i32 s49, 0x7000
	s_nop 0
	v_addc_co_u32_e32 v17, vcc, 0, v3, vcc
	v_add_co_u32_e32 v30, vcc, s49, v2
	s_mov_b32 s49, 0x9000
	s_nop 0
	v_addc_co_u32_e32 v31, vcc, 0, v3, vcc
	v_add_co_u32_e32 v34, vcc, s49, v2
	s_mov_b32 s49, 0xa000
	s_nop 0
	v_addc_co_u32_e32 v35, vcc, 0, v3, vcc
	flat_load_ushort v13, v[20:21]
	v_add_co_u32_e32 v56, vcc, s49, v2
	flat_load_ushort v27, v[16:17]
	flat_load_ushort v28, v[16:17] offset:1024
	s_nop 0
	flat_load_ushort v16, v[20:21] offset:1024
	v_addc_co_u32_e32 v57, vcc, 0, v3, vcc
	s_movk_i32 s49, 0x2000
	flat_load_ushort v29, v[30:31] offset:2048
	s_nop 0
	flat_load_ushort v30, v[30:31] offset:3072
	s_nop 0
	flat_load_ushort v17, v[20:21] offset:2048
	v_add_co_u32_e32 v112, vcc, s49, v4
	flat_load_ushort v33, v[34:35]
	s_nop 0
	flat_load_ushort v34, v[34:35] offset:1024
	s_nop 0
	flat_load_ushort v20, v[20:21] offset:3072
	v_addc_co_u32_e32 v113, vcc, 0, v5, vcc
	flat_load_ushort v35, v[56:57] offset:2048
	flat_load_ushort v55, v[56:57] offset:3072
	flat_load_ushort v21, v[112:113]
	v_cvt_f32_f16_e32 v9, v9
	v_add_f32_e32 v7, v8, v7
	v_add_co_u32_e32 v58, vcc, s85, v2
	v_add_f32_e32 v9, v7, v9
	s_nop 0
	v_addc_co_u32_e32 v59, vcc, 0, v3, vcc
	v_add_co_u32_e32 v110, vcc, s86, v2
	s_mov_b32 s49, s67
	s_nop 0
	v_addc_co_u32_e32 v111, vcc, 0, v3, vcc
	s_waitcnt vmcnt(0) lgkmcnt(0)
	v_cvt_f32_f16_e32 v12, v12
	v_add_f32_e32 v12, v9, v12
	v_cvt_f32_f16_e32 v13, v13
	v_cvt_f32_f16_e32 v16, v16
	v_add_f32_e32 v13, v12, v13
	v_cvt_f32_f16_e32 v17, v17
	v_add_f32_e32 v16, v13, v16
	v_cvt_f32_f16_e32 v20, v20
	v_add_f32_e32 v17, v16, v17
	v_cvt_f32_f16_e32 v21, v21
	v_add_f32_e32 v20, v17, v20
	v_add_f32_e32 v22, v20, v21
	flat_load_ushort v56, v[58:59]
	flat_load_ushort v57, v[58:59] offset:1024
	flat_load_ushort v21, v[112:113] offset:1024
	s_nop 0
	flat_load_ushort v58, v[110:111] offset:2048
	flat_load_ushort v59, v[110:111] offset:3072
	flat_load_ushort v25, v[112:113] offset:2048
	v_add_co_u32_e32 v110, vcc, s87, v2
	s_waitcnt vmcnt(0) lgkmcnt(0)
	v_cvt_f32_f16_e32 v21, v21
	v_addc_co_u32_e32 v111, vcc, 0, v3, vcc
	flat_load_ushort v109, v[110:111]
	s_nop 0
	flat_load_ushort v110, v[110:111] offset:1024
	s_nop 0
	flat_load_ushort v26, v[112:113] offset:3072
	v_add_co_u32_e32 v112, vcc, s88, v2
	v_cvt_f32_f16_e32 v25, v25
	s_nop 0
	v_addc_co_u32_e32 v113, vcc, 0, v3, vcc
	v_add_co_u32_e32 v120, vcc, s84, v4
	flat_load_ushort v111, v[112:113] offset:2048
	s_nop 0
	flat_load_ushort v112, v[112:113] offset:3072
	v_addc_co_u32_e32 v121, vcc, 0, v5, vcc
	v_add_co_u32_e32 v114, vcc, s89, v2
	flat_load_ushort v4, v[120:121]
	s_nop 0
	v_addc_co_u32_e32 v115, vcc, 0, v3, vcc
	v_add_co_u32_e32 v116, vcc, s90, v2
	flat_load_ushort v113, v[114:115]
	s_nop 0
	flat_load_ushort v114, v[114:115] offset:1024
	s_nop 0
	flat_load_ushort v5, v[120:121] offset:1024
	v_addc_co_u32_e32 v117, vcc, 0, v3, vcc
	v_add_co_u32_e32 v118, vcc, s91, v2
	flat_load_ushort v115, v[116:117] offset:2048
	s_nop 0
	flat_load_ushort v116, v[116:117] offset:3072
	s_nop 0
	flat_load_ushort v31, v[120:121] offset:2048
	v_addc_co_u32_e32 v119, vcc, 0, v3, vcc
	flat_load_ushort v117, v[118:119]
	s_nop 0
	flat_load_ushort v118, v[118:119] offset:1024
	s_nop 0
	flat_load_ushort v32, v[120:121] offset:3072
	v_add_f32_e32 v21, v22, v21
	v_add_f32_e32 v25, v21, v25
	v_add_co_u32_e32 v120, vcc, s92, v2
	v_add_u32_e32 v119, v62, v69
	s_nop 0
	v_addc_co_u32_e32 v121, vcc, 0, v3, vcc
	flat_load_ushort v2, v[120:121] offset:2048
	flat_load_ushort v3, v[120:121] offset:3072
	v_mad_i64_i32 v[120:121], vcc, v53, s3, v[0:1]
	v_lshl_add_u64 v[120:121], v[120:121], 0, s[48:49]
	v_mov_b32_e32 v53, v37
	v_lshl_add_u64 v[120:121], v[120:121], 0, v[52:53]
	s_waitcnt vmcnt(0) lgkmcnt(0)
	v_cvt_f32_f16_e32 v26, v26
	v_add_f32_e32 v26, v25, v26
	v_cvt_f32_f16_e32 v4, v4
	v_add_f32_e32 v4, v26, v4
	v_cvt_f32_f16_e32 v5, v5
	v_add_f32_e32 v5, v4, v5
	v_cvt_f32_f16_e32 v31, v31
	v_cvt_f32_f16_e32 v32, v32
	v_add_f32_e32 v31, v5, v31
	v_add_f32_e32 v32, v31, v32
	ds_write_b32 v61, v32
	global_load_dwordx4 v[184:187], v[120:121], off offset:2048
	v_mov_b32_e32 v232, v119
	v_add_u32_e32 v120, s33, v70
	v_mad_i64_i32 v[120:121], vcc, v120, s3, v[0:1]
	v_lshl_add_u64 v[120:121], v[120:121], 0, s[48:49]
	v_lshl_add_u64 v[120:121], v[120:121], 0, v[52:53]
	global_load_dwordx4 v[188:191], v[120:121], off offset:2048
	v_mov_b32_e32 v233, v124
	v_add_u32_e32 v120, s33, v72
	v_mad_i64_i32 v[120:121], vcc, v120, s3, v[0:1]
	v_lshl_add_u64 v[120:121], v[120:121], 0, s[48:49]
	v_lshl_add_u64 v[120:121], v[120:121], 0, v[52:53]
	global_load_dwordx4 v[192:195], v[120:121], off offset:2048
	v_mov_b32_e32 v234, v119
	v_add_u32_e32 v119, s33, v73
	v_mad_i64_i32 v[0:1], vcc, v119, s3, v[0:1]
	v_lshl_add_u64 v[0:1], v[0:1], 0, s[48:49]
	v_lshl_add_u64 v[0:1], v[0:1], 0, v[52:53]
	global_load_dwordx4 v[196:199], v[0:1], off offset:2048
	v_add_u32_e32 v0, v62, v74
	v_add_u32_e32 v53, v63, v69
	v_add_u32_e32 v119, v63, v71
	v_mov_b32_e32 v235, v0
	v_lshl_add_u64 v[0:1], v[44:45], 0, v[38:39]
	v_add_co_u32_e32 v120, vcc, s93, v0
	s_nop 1
	v_addc_co_u32_e32 v121, vcc, 0, v1, vcc
	global_load_dwordx4 v[200:203], v[120:121], off
	v_mov_b32_e32 v236, v53
	v_lshl_add_u64 v[120:121], v[50:51], 0, v[38:39]
	global_load_dwordx4 v[204:207], v[120:121], off
	v_mov_b32_e32 v237, v119
	v_add_co_u32_e32 v120, vcc, s94, v0
	v_add_u32_e32 v119, v63, v74
	s_nop 0
	v_addc_co_u32_e32 v121, vcc, 0, v1, vcc
	global_load_dwordx4 v[208:211], v[120:121], off
	v_mov_b32_e32 v238, v53
	v_lshl_add_u64 v[120:121], v[48:49], 0, v[38:39]
	global_load_dwordx4 v[212:215], v[120:121], off
	v_mov_b32_e32 v239, v119
	v_add_co_u32_e32 v120, vcc, s95, v0
	s_nop 1
	v_addc_co_u32_e32 v121, vcc, 0, v1, vcc
	global_load_dwordx4 v[216:219], v[120:121], off
	v_add_co_u32_e32 v0, vcc, 0x9c0c000, v0
	v_mov_b32_e32 v240, v53
	v_lshl_add_u64 v[120:121], v[46:47], 0, v[38:39]
	global_load_dwordx4 v[220:223], v[120:121], off
	v_addc_co_u32_e32 v1, vcc, 0, v1, vcc
	v_mov_b32_e32 v241, v79
	global_load_dwordx4 v[224:227], v[0:1], off
	v_lshl_add_u64 v[0:1], v[42:43], 0, v[38:39]
	v_mov_b32_e32 v242, v53
	global_load_dwordx4 v[228:231], v[0:1], off
	v_mov_b32_e32 v243, v80
	s_waitcnt vmcnt(0)
	ds_write_b128 v232, v[184:187] offset:34816
	ds_write_b128 v233, v[188:191] offset:34816
	ds_write_b128 v234, v[192:195] offset:53248
	ds_write_b128 v235, v[196:199] offset:34816
	ds_write_b128 v236, v[200:203]
	ds_write_b128 v237, v[204:207]
	ds_write_b128 v238, v[208:211] offset:18432
	ds_write_b128 v239, v[212:215]
	ds_write_b128 v240, v[216:219] offset:36864
	ds_write_b128 v241, v[220:223]
	ds_write_b128 v242, v[224:227] offset:55296
	ds_write_b128 v243, v[228:231]
	s_waitcnt lgkmcnt(0)
	s_barrier
	s_and_saveexec_b64 s[48:49], s[6:7]
	s_cbranch_execnz .LBB0_1522
	s_or_b64 exec, exec, s[48:49]
	s_and_saveexec_b64 s[48:49], s[8:9]
	s_cbranch_execnz .LBB0_1523
